# gather: tasks with t>=255 run a copy of the 8-chunk body without the per-slot validity masks
# speedup vs baseline: 1.0015x; 1.0015x over previous
.LBB0_978:
	s_abs_i32 s10, s70
	s_mul_hi_u32 s12, s10, s56
	s_mul_i32 s14, s12, s45
	s_ashr_i32 s8, s70, 31
	s_sub_i32 s10, s10, s14
	s_andn2_b32 s13, 0x200, s69
	s_xor_b32 s8, s8, s55
	s_add_i32 s14, s12, 1
	s_sub_i32 s15, s10, s45
	s_cmp_ge_u32 s10, s45
	s_cselect_b32 s12, s14, s12
	s_cselect_b32 s10, s15, s10
	s_add_i32 s14, s12, 1
	s_cmp_ge_u32 s10, s45
	s_cselect_b32 s10, s14, s12
	s_xor_b32 s10, s10, s8
	s_sub_i32 s12, s10, s8
	s_lshl_b32 s8, s12, s24
	s_mul_i32 s12, s57, s12
	s_add_i32 s12, s70, s12
	s_add_i32 s8, s8, s41
	s_mul_i32 s12, s12, s25
	s_mov_b32 s11, s70
	s_ashr_i32 s10, s8, 2
	s_and_b32 s8, s8, 3
	s_add_i32 s12, s12, s40
	s_add_i32 s70, s70, 1
	s_cmp_lt_i32 s70, s43
	s_cselect_b32 s33, s70, s11
	s_abs_i32 s14, s33
	s_mul_hi_u32 s15, s14, s56
	s_mul_i32 s16, s15, s45
	s_ashr_i32 s11, s33, 31
	s_sub_i32 s14, s14, s16
	s_xor_b32 s11, s11, s55
	s_add_i32 s16, s15, 1
	s_sub_i32 s17, s14, s45
	s_cmp_ge_u32 s14, s45
	s_cselect_b32 s15, s16, s15
	s_cselect_b32 s14, s17, s14
	s_add_i32 s16, s15, 1
	s_cmp_ge_u32 s14, s45
	s_cselect_b32 s14, s16, s15
	s_xor_b32 s14, s14, s11
	s_sub_i32 s71, s14, s11
	s_lshl_b32 s11, s71, s24
	s_add_i32 s11, s11, s41
	s_ashr_i32 s72, s11, 2
	s_and_b32 s82, s11, 3
	s_ashr_i32 s11, s10, 31
	s_lshl_b64 s[14:15], s[10:11], 22
	s_add_u32 s22, s80, s14
	s_addc_u32 s23, s81, s15
	s_ashr_i32 s73, s72, 31
	s_lshl_b64 s[16:17], s[72:73], 22
	s_add_u32 s74, s80, s16
	s_addc_u32 s75, s81, s17
	s_add_i32 s83, s47, s13
	s_add_u32 s13, s37, s14
	s_addc_u32 s14, s79, s15
	s_lshl_b32 s15, s8, 7
	s_add_u32 s18, s13, s15
	s_addc_u32 s19, s14, 0
	s_add_u32 s22, s22, s15
	s_addc_u32 s23, s23, 0
	s_add_u32 s13, s37, s16
	s_addc_u32 s15, s79, s17
	s_lshl_b32 s16, s82, 7
	s_add_u32 s14, s13, s16
	s_addc_u32 s15, s15, 0
	s_add_u32 s16, s74, s16
	s_mul_i32 s71, s71, s42
	s_addc_u32 s17, s75, 0
	s_sub_i32 s33, s33, s71
	s_mul_i32 s33, s33, s25
	s_add_i32 s33, s33, s40
	s_min_i32 s13, s12, 0xff
	s_lshl_b64 s[72:73], s[72:73], 13
	s_ashr_i32 s71, s33, 31
	s_add_u32 s72, s72, s33
	s_addc_u32 s73, s73, s71
	s_mul_i32 s71, s73, 0x1200
	s_mul_hi_u32 s74, s72, 0x1200
	s_add_i32 s71, s74, s71
	s_mul_i32 s74, s72, 0x1200
	s_add_u32 s74, s38, s74
	s_addc_u32 s75, s39, s71
	s_waitcnt lgkmcnt(0)
	v_lshl_or_b32 v42, s82, 9, v62
	v_lshlrev_b32_e32 v34, 9, v32
	v_lshl_add_u64 v[14:15], s[74:75], 0, v[42:43]
	s_cmpk_gt_i32 s33, 0xff
	v_and_b32_e32 v42, 0x1fffe00, v34
	v_mov_b32_e32 v57, v43
	s_cselect_b64 vcc, -1, 0
	s_lshl_b64 s[72:73], s[72:73], 9
	v_lshl_add_u64 v[34:35], s[18:19], 0, v[42:43]
	s_mov_b32 m0, s44
	v_lshl_add_u64 v[14:15], v[14:15], 0, v[56:57]
	v_lshl_add_u64 v[16:17], v[54:55], 0, s[72:73]
	v_lshl_add_u64 v[34:35], v[34:35], 0, v[44:45]
	global_load_dwordx2 v[30:31], v[16:17], off
	global_load_dwordx4 v[18:21], v[14:15], off
	s_nop 0
	global_load_dwordx4 v[14:17], v[14:15], off offset:64
	s_nop 0
	global_load_lds_dwordx4 v[34:35], off
	v_lshl_add_u64 v[34:35], s[22:23], 0, v[42:43]
	v_lshl_add_u64 v[34:35], v[34:35], 0, v[52:53]
	s_mov_b32 m0, s58
	v_lshlrev_b32_sdwa v42, v64, v32 dst_sel:DWORD dst_unused:UNUSED_PAD src0_sel:DWORD src1_sel:WORD_1
	global_load_lds_dwordx4 v[34:35], off
	v_lshl_add_u64 v[34:35], s[18:19], 0, v[42:43]
	v_lshl_add_u64 v[34:35], v[34:35], 0, v[50:51]
	s_mov_b32 m0, s59
	v_lshlrev_b32_e32 v32, 9, v33
	global_load_lds_dwordx4 v[34:35], off
	v_lshl_add_u64 v[34:35], s[22:23], 0, v[42:43]
	v_lshl_add_u64 v[34:35], v[34:35], 0, v[52:53]
	s_mov_b32 m0, s60
	v_and_b32_e32 v42, 0x1fffe00, v32
	global_load_lds_dwordx4 v[34:35], off
	v_lshl_add_u64 v[34:35], s[18:19], 0, v[42:43]
	v_lshl_add_u64 v[34:35], v[34:35], 0, v[48:49]
	s_mov_b32 m0, s61
	s_nop 0
	global_load_lds_dwordx4 v[34:35], off
	v_lshl_add_u64 v[34:35], s[22:23], 0, v[42:43]
	v_lshlrev_b32_sdwa v42, v64, v33 dst_sel:DWORD dst_unused:UNUSED_PAD src0_sel:DWORD src1_sel:WORD_1
	v_lshl_add_u64 v[34:35], v[34:35], 0, v[52:53]
	s_mov_b32 m0, s64
	v_lshl_add_u64 v[32:33], s[18:19], 0, v[42:43]
	global_load_lds_dwordx4 v[34:35], off
	v_lshl_add_u64 v[32:33], v[32:33], 0, v[46:47]
	s_mov_b32 m0, s65
	s_nop 0
	global_load_lds_dwordx4 v[32:33], off
	v_lshl_add_u64 v[32:33], s[22:23], 0, v[42:43]
	v_lshl_add_u64 v[32:33], v[32:33], 0, v[52:53]
	s_mov_b32 m0, s66
	s_nop 0
	global_load_lds_dwordx4 v[32:33], off
	s_waitcnt vmcnt(8)
	ds_read_b128 v[36:39], v145
	ds_read_b128 v[162:165], v149
	ds_read_b128 v[166:169], v151
	ds_read_b128 v[170:173], v153
	s_waitcnt lgkmcnt(0)
	v_mov_b64_e32 v[34:35], v[28:29]
	v_mov_b64_e32 v[32:33], v[26:27]
	v_add_u32_e32 v28, s83, v63
	v_lshl_add_u32 v29, v1, 1, s83
	s_waitcnt vmcnt(0)
	v_cndmask_b32_e32 v26, v60, v30, vcc
	v_cndmask_b32_e32 v27, v61, v31, vcc
	v_mfma_f32_16x16x32_bf16 v[36:39], v[36:39], v[10:13], 0
	s_cmpk_lt_i32 s12, 0xff
	s_cbranch_scc1 .Lg_masked
	s_mov_b32 m0, s46
	v_mfma_f32_16x16x32_bf16 v[36:39], v[162:165], v[6:9], v[36:39]
	v_mfma_f32_16x16x32_bf16 v[162:165], v[166:169], v[10:13], 0
	v_mfma_f32_16x16x32_bf16 v[162:165], v[170:173], v[6:9], v[162:165]
	s_nop 5
	v_mul_f32_e32 v30, 0x3fb8aa3b, v36
	v_exp_f32_e32 v40, v30
	s_nop 0
	v_mul_f32_e32 v30, 0x3fb8aa3b, v37
	v_mul_f32_e32 v31, 0x3fb8aa3b, v162
	v_exp_f32_e32 v41, v31
	v_exp_f32_e32 v57, v30
	s_nop 0
	v_mul_f32_e32 v31, 0x3fb8aa3b, v163
	v_exp_f32_e32 v59, v31
	s_nop 1
	v_mul_f32_e32 v30, 0x3fb8aa3b, v38
	v_exp_f32_e32 v155, v30
	v_cvt_pk_bf16_f32 v36, v40, v57
	s_nop 0
	v_mul_f32_e32 v31, 0x3fb8aa3b, v164
	v_exp_f32_e32 v156, v31
	s_nop 1
	v_mul_f32_e32 v30, 0x3fb8aa3b, v39
	v_exp_f32_e32 v157, v30
	s_nop 0
	v_mul_f32_e32 v31, 0x3fb8aa3b, v165
	v_exp_f32_e32 v158, v31
	s_nop 1
	v_lshlrev_b32_e32 v30, 9, v22
	v_and_b32_e32 v42, 0x1fffe00, v30
	v_cvt_pk_bf16_f32 v37, v155, v157
	v_cvt_pk_bf16_f32 v38, v41, v59
	s_nop 0
	v_lshl_add_u64 v[30:31], s[18:19], 0, v[42:43]
	v_cvt_pk_bf16_f32 v39, v156, v158
	ds_read_b64_tr_b16 v[174:175], v73
	ds_read_b64_tr_b16 v[176:177], v74
	ds_read_b64_tr_b16 v[170:171], v75
	ds_read_b64_tr_b16 v[172:173], v76
	ds_read_b64_tr_b16 v[166:167], v77
	ds_read_b64_tr_b16 v[168:169], v78
	ds_read_b64_tr_b16 v[162:163], v79
	ds_read_b64_tr_b16 v[164:165], v80
	s_waitcnt lgkmcnt(0)
	v_lshl_add_u64 v[30:31], v[30:31], 0, v[44:45]
	global_load_lds_dwordx4 v[30:31], off
	v_lshl_add_u64 v[30:31], s[22:23], 0, v[42:43]
	v_lshl_add_u64 v[30:31], v[30:31], 0, v[52:53]
	s_mov_b32 m0, s48
	v_lshlrev_b32_sdwa v42, v64, v22 dst_sel:DWORD dst_unused:UNUSED_PAD src0_sel:DWORD src1_sel:WORD_1
	global_load_lds_dwordx4 v[30:31], off
	v_lshl_add_u64 v[30:31], s[18:19], 0, v[42:43]
	v_lshl_add_u64 v[30:31], v[30:31], 0, v[50:51]
	s_mov_b32 m0, s49
	v_lshlrev_b32_e32 v22, 9, v23
	global_load_lds_dwordx4 v[30:31], off
	v_lshl_add_u64 v[30:31], s[22:23], 0, v[42:43]
	v_lshl_add_u64 v[30:31], v[30:31], 0, v[52:53]
	s_mov_b32 m0, s50
	v_and_b32_e32 v42, 0x1fffe00, v22
	global_load_lds_dwordx4 v[30:31], off
	v_lshl_add_u64 v[30:31], s[18:19], 0, v[42:43]
	v_lshl_add_u64 v[30:31], v[30:31], 0, v[48:49]
	s_mov_b32 m0, s51
	v_mfma_f32_16x16x32_bf16 v[174:177], v[36:39], v[174:177], 0
	global_load_lds_dwordx4 v[30:31], off
	v_lshl_add_u64 v[30:31], s[22:23], 0, v[42:43]
	v_lshlrev_b32_sdwa v42, v64, v23 dst_sel:DWORD dst_unused:UNUSED_PAD src0_sel:DWORD src1_sel:WORD_1
	v_lshl_add_u64 v[30:31], v[30:31], 0, v[52:53]
	s_mov_b32 m0, s52
	v_lshl_add_u64 v[22:23], s[18:19], 0, v[42:43]
	global_load_lds_dwordx4 v[30:31], off
	v_lshl_add_u64 v[22:23], v[22:23], 0, v[46:47]
	s_mov_b32 m0, s53
	v_mfma_f32_16x16x32_bf16 v[170:173], v[36:39], v[170:173], 0
	global_load_lds_dwordx4 v[22:23], off
	v_lshl_add_u64 v[22:23], s[22:23], 0, v[42:43]
	v_lshl_add_u64 v[22:23], v[22:23], 0, v[52:53]
	s_mov_b32 m0, s54
	v_mfma_f32_16x16x32_bf16 v[166:169], v[36:39], v[166:169], 0
	global_load_lds_dwordx4 v[22:23], off
	s_waitcnt vmcnt(8)
	ds_read_b128 v[178:181], v145 offset:8192
	ds_read_b128 v[182:185], v149 offset:8192
	ds_read_b128 v[186:189], v151 offset:8192
	ds_read_b128 v[190:193], v153 offset:8192
	v_add_f32_e32 v22, v40, v41
	v_add_f32_e32 v22, 0, v22
	v_add_f32_e32 v23, v57, v59
	v_mfma_f32_16x16x32_bf16 v[36:39], v[36:39], v[162:165], 0
	v_add_f32_e32 v22, v23, v22
	v_add_f32_e32 v23, v155, v156
	v_add_f32_e32 v22, v23, v22
	v_add_f32_e32 v23, v157, v158
	v_add_f32_e32 v30, v23, v22
	s_waitcnt lgkmcnt(0)
	v_mfma_f32_16x16x32_bf16 v[162:165], v[178:181], v[10:13], 0
	s_mov_b32 m0, s44
	v_mfma_f32_16x16x32_bf16 v[178:181], v[186:189], v[10:13], 0
	v_mfma_f32_16x16x32_bf16 v[162:165], v[182:185], v[6:9], v[162:165]
	v_mfma_f32_16x16x32_bf16 v[178:181], v[190:193], v[6:9], v[178:181]
	s_nop 6
	v_mul_f32_e32 v22, 0x3fb8aa3b, v162
	v_exp_f32_e32 v22, v22
	v_mul_f32_e32 v23, 0x3fb8aa3b, v178
	v_exp_f32_e32 v23, v23
	v_mov_b32_e32 v31, v22
	v_mul_f32_e32 v22, 0x3fb8aa3b, v163
	v_exp_f32_e32 v22, v22
	s_nop 0
	v_mov_b32_e32 v40, v23
	v_mul_f32_e32 v23, 0x3fb8aa3b, v179
	v_exp_f32_e32 v23, v23
	s_nop 1
	v_mov_b32_e32 v41, v22
	v_mul_f32_e32 v22, 0x3fb8aa3b, v164
	v_exp_f32_e32 v22, v22
	v_cvt_pk_bf16_f32 v162, v31, v41
	v_add_f32_e32 v31, v31, v40
	v_mov_b32_e32 v57, v23
	v_mul_f32_e32 v23, 0x3fb8aa3b, v180
	v_exp_f32_e32 v23, v23
	v_add_f32_e32 v30, v30, v31
	v_add_f32_e32 v31, v41, v57
	v_mov_b32_e32 v59, v22
	v_mul_f32_e32 v22, 0x3fb8aa3b, v165
	v_exp_f32_e32 v22, v22
	v_add_f32_e32 v30, v31, v30
	v_mov_b32_e32 v155, v23
	v_mul_f32_e32 v23, 0x3fb8aa3b, v181
	v_exp_f32_e32 v23, v23
	v_add_f32_e32 v31, v59, v155
	v_add_f32_e32 v30, v31, v30
	v_mov_b32_e32 v156, v22
	v_lshlrev_b32_e32 v22, 9, v24
	v_and_b32_e32 v42, 0x1fffe00, v22
	v_cvt_pk_bf16_f32 v163, v59, v156
	v_cvt_pk_bf16_f32 v164, v40, v57
	s_nop 0
	v_mov_b32_e32 v157, v23
	v_lshl_add_u64 v[22:23], s[18:19], 0, v[42:43]
	v_cvt_pk_bf16_f32 v165, v155, v157
	ds_read_b64_tr_b16 v[190:191], v89
	ds_read_b64_tr_b16 v[192:193], v90
	ds_read_b64_tr_b16 v[186:187], v91
	ds_read_b64_tr_b16 v[188:189], v92
	ds_read_b64_tr_b16 v[182:183], v93
	ds_read_b64_tr_b16 v[184:185], v94
	ds_read_b64_tr_b16 v[178:179], v95
	ds_read_b64_tr_b16 v[180:181], v96
	s_waitcnt lgkmcnt(0)
	v_lshl_add_u64 v[22:23], v[22:23], 0, v[44:45]
	global_load_lds_dwordx4 v[22:23], off
	v_lshl_add_u64 v[22:23], s[22:23], 0, v[42:43]
	v_lshl_add_u64 v[22:23], v[22:23], 0, v[52:53]
	s_mov_b32 m0, s58
	v_lshlrev_b32_sdwa v42, v64, v24 dst_sel:DWORD dst_unused:UNUSED_PAD src0_sel:DWORD src1_sel:WORD_1
	global_load_lds_dwordx4 v[22:23], off
	v_lshl_add_u64 v[22:23], s[18:19], 0, v[42:43]
	v_lshl_add_u64 v[22:23], v[22:23], 0, v[50:51]
	s_mov_b32 m0, s59
	v_mfma_f32_16x16x32_bf16 v[170:173], v[162:165], v[186:189], v[170:173]
	global_load_lds_dwordx4 v[22:23], off
	v_lshl_add_u64 v[22:23], s[22:23], 0, v[42:43]
	v_lshl_add_u64 v[22:23], v[22:23], 0, v[52:53]
	s_mov_b32 m0, s60
	v_mfma_f32_16x16x32_bf16 v[166:169], v[162:165], v[182:185], v[166:169]
	global_load_lds_dwordx4 v[22:23], off
	v_lshlrev_b32_e32 v22, 9, v25
	v_and_b32_e32 v42, 0x1fffe00, v22
	v_lshl_add_u64 v[22:23], s[18:19], 0, v[42:43]
	v_lshl_add_u64 v[22:23], v[22:23], 0, v[48:49]
	s_mov_b32 m0, s61
	v_mfma_f32_16x16x32_bf16 v[36:39], v[162:165], v[178:181], v[36:39]
	global_load_lds_dwordx4 v[22:23], off
	v_lshl_add_u64 v[22:23], s[22:23], 0, v[42:43]
	v_lshl_add_u64 v[22:23], v[22:23], 0, v[52:53]
	s_mov_b32 m0, s64
	v_lshlrev_b32_sdwa v42, v64, v25 dst_sel:DWORD dst_unused:UNUSED_PAD src0_sel:DWORD src1_sel:WORD_1
	global_load_lds_dwordx4 v[22:23], off
	v_lshl_add_u64 v[22:23], s[18:19], 0, v[42:43]
	v_lshl_add_u64 v[22:23], v[22:23], 0, v[46:47]
	s_mov_b32 m0, s65
	v_add_f32_e32 v31, v156, v157
	global_load_lds_dwordx4 v[22:23], off
	v_lshl_add_u64 v[22:23], s[22:23], 0, v[42:43]
	v_lshl_add_u64 v[22:23], v[22:23], 0, v[52:53]
	s_mov_b32 m0, s66
	v_add_f32_e32 v40, v31, v30
	global_load_lds_dwordx4 v[22:23], off
	s_waitcnt vmcnt(8)
	v_mfma_f32_16x16x32_bf16 v[22:25], v[162:165], v[190:193], v[174:177]
	s_nop 2
	ds_read_b128 v[174:177], v145
	ds_read_b128 v[182:185], v149
	ds_read_b128 v[186:189], v151
	ds_read_b128 v[190:193], v153
	s_waitcnt lgkmcnt(0)
	v_mfma_f32_16x16x32_bf16 v[162:165], v[174:177], v[10:13], 0
	s_mov_b32 m0, s46
	v_mfma_f32_16x16x32_bf16 v[174:177], v[186:189], v[10:13], 0
	v_mfma_f32_16x16x32_bf16 v[162:165], v[182:185], v[6:9], v[162:165]
	v_mfma_f32_16x16x32_bf16 v[174:177], v[190:193], v[6:9], v[174:177]
	s_nop 6
	v_mul_f32_e32 v30, 0x3fb8aa3b, v162
	v_exp_f32_e32 v41, v30
	v_mul_f32_e32 v31, 0x3fb8aa3b, v174
	v_exp_f32_e32 v57, v31
	v_mul_f32_e32 v30, 0x3fb8aa3b, v163
	v_exp_f32_e32 v59, v30
	s_nop 0
	v_mul_f32_e32 v31, 0x3fb8aa3b, v175
	v_exp_f32_e32 v155, v31
	s_nop 1
	v_mul_f32_e32 v30, 0x3fb8aa3b, v164
	v_exp_f32_e32 v156, v30
	v_cvt_pk_bf16_f32 v162, v41, v59
	s_nop 0
	v_mul_f32_e32 v31, 0x3fb8aa3b, v176
	v_exp_f32_e32 v157, v31
	s_nop 1
	v_mul_f32_e32 v30, 0x3fb8aa3b, v165
	v_exp_f32_e32 v158, v30
	s_nop 0
	v_mul_f32_e32 v31, 0x3fb8aa3b, v177
	v_exp_f32_e32 v160, v31
	s_nop 1
	v_lshlrev_b32_e32 v30, 9, v2
	v_and_b32_e32 v42, 0x1fffe00, v30
	v_cvt_pk_bf16_f32 v163, v156, v158
	v_cvt_pk_bf16_f32 v164, v57, v155
	s_nop 0
	v_lshl_add_u64 v[30:31], s[18:19], 0, v[42:43]
	v_cvt_pk_bf16_f32 v165, v157, v160
	ds_read_b64_tr_b16 v[186:187], v73
	ds_read_b64_tr_b16 v[188:189], v74
	ds_read_b64_tr_b16 v[182:183], v75
	ds_read_b64_tr_b16 v[184:185], v76
	ds_read_b64_tr_b16 v[178:179], v77
	ds_read_b64_tr_b16 v[180:181], v78
	ds_read_b64_tr_b16 v[174:175], v79
	ds_read_b64_tr_b16 v[176:177], v80
	s_waitcnt lgkmcnt(0)
	v_lshl_add_u64 v[30:31], v[30:31], 0, v[44:45]
	global_load_lds_dwordx4 v[30:31], off
	v_lshl_add_u64 v[30:31], s[22:23], 0, v[42:43]
	v_lshl_add_u64 v[30:31], v[30:31], 0, v[52:53]
	s_mov_b32 m0, s48
	v_lshlrev_b32_sdwa v42, v64, v2 dst_sel:DWORD dst_unused:UNUSED_PAD src0_sel:DWORD src1_sel:WORD_1
	global_load_lds_dwordx4 v[30:31], off
	v_lshl_add_u64 v[30:31], s[18:19], 0, v[42:43]
	v_lshl_add_u64 v[30:31], v[30:31], 0, v[50:51]
	s_mov_b32 m0, s49
	v_lshlrev_b32_e32 v2, 9, v3
	global_load_lds_dwordx4 v[30:31], off
	v_lshl_add_u64 v[30:31], s[22:23], 0, v[42:43]
	v_lshl_add_u64 v[30:31], v[30:31], 0, v[52:53]
	s_mov_b32 m0, s50
	v_and_b32_e32 v42, 0x1fffe00, v2
	global_load_lds_dwordx4 v[30:31], off
	v_lshl_add_u64 v[30:31], s[18:19], 0, v[42:43]
	v_lshl_add_u64 v[30:31], v[30:31], 0, v[48:49]
	s_mov_b32 m0, s51
	v_mfma_f32_16x16x32_bf16 v[22:25], v[162:165], v[186:189], v[22:25]
	global_load_lds_dwordx4 v[30:31], off
	v_lshl_add_u64 v[30:31], s[22:23], 0, v[42:43]
	v_lshlrev_b32_sdwa v42, v64, v3 dst_sel:DWORD dst_unused:UNUSED_PAD src0_sel:DWORD src1_sel:WORD_1
	v_lshl_add_u64 v[30:31], v[30:31], 0, v[52:53]
	s_mov_b32 m0, s52
	v_lshl_add_u64 v[2:3], s[18:19], 0, v[42:43]
	global_load_lds_dwordx4 v[30:31], off
	v_lshl_add_u64 v[2:3], v[2:3], 0, v[46:47]
	s_mov_b32 m0, s53
	v_mfma_f32_16x16x32_bf16 v[170:173], v[162:165], v[182:185], v[170:173]
	global_load_lds_dwordx4 v[2:3], off
	v_lshl_add_u64 v[2:3], s[22:23], 0, v[42:43]
	v_lshl_add_u64 v[2:3], v[2:3], 0, v[52:53]
	s_mov_b32 m0, s54
	v_mfma_f32_16x16x32_bf16 v[166:169], v[162:165], v[178:181], v[166:169]
	global_load_lds_dwordx4 v[2:3], off
	s_waitcnt vmcnt(8)
	ds_read_b128 v[178:181], v145 offset:8192
	ds_read_b128 v[182:185], v149 offset:8192
	ds_read_b128 v[186:189], v151 offset:8192
	ds_read_b128 v[190:193], v153 offset:8192
	v_add_f32_e32 v2, v41, v57
	v_add_f32_e32 v2, v40, v2
	v_add_f32_e32 v3, v59, v155
	v_mfma_f32_16x16x32_bf16 v[36:39], v[162:165], v[174:177], v[36:39]
	v_add_f32_e32 v2, v3, v2
	v_add_f32_e32 v3, v156, v157
	v_add_f32_e32 v2, v3, v2
	v_add_f32_e32 v3, v158, v160
	v_add_f32_e32 v30, v3, v2
	s_waitcnt lgkmcnt(0)
	v_mfma_f32_16x16x32_bf16 v[162:165], v[178:181], v[10:13], 0
	s_mov_b32 m0, s44
	v_mfma_f32_16x16x32_bf16 v[174:177], v[186:189], v[10:13], 0
	v_mfma_f32_16x16x32_bf16 v[162:165], v[182:185], v[6:9], v[162:165]
	v_mfma_f32_16x16x32_bf16 v[174:177], v[190:193], v[6:9], v[174:177]
	s_nop 6
	v_mul_f32_e32 v2, 0x3fb8aa3b, v162
	v_exp_f32_e32 v2, v2
	v_mul_f32_e32 v3, 0x3fb8aa3b, v174
	v_exp_f32_e32 v3, v3
	v_mov_b32_e32 v31, v2
	v_mul_f32_e32 v2, 0x3fb8aa3b, v163
	v_exp_f32_e32 v2, v2
	s_nop 0
	v_mov_b32_e32 v40, v3
	v_mul_f32_e32 v3, 0x3fb8aa3b, v175
	v_exp_f32_e32 v3, v3
	s_nop 1
	v_mov_b32_e32 v41, v2
	v_mul_f32_e32 v2, 0x3fb8aa3b, v164
	v_exp_f32_e32 v2, v2
	v_cvt_pk_bf16_f32 v162, v31, v41
	s_nop 0
	v_mov_b32_e32 v57, v3
	v_mul_f32_e32 v3, 0x3fb8aa3b, v176
	v_exp_f32_e32 v3, v3
	s_nop 1
	v_mov_b32_e32 v59, v2
	v_mul_f32_e32 v2, 0x3fb8aa3b, v165
	v_exp_f32_e32 v2, v2
	s_nop 0
	v_mov_b32_e32 v155, v3
	v_mul_f32_e32 v3, 0x3fb8aa3b, v177
	v_exp_f32_e32 v3, v3
	s_nop 1
	v_mov_b32_e32 v156, v2
	v_lshlrev_b32_e32 v2, 9, v4
	v_and_b32_e32 v42, 0x1fffe00, v2
	v_cvt_pk_bf16_f32 v163, v59, v156
	v_cvt_pk_bf16_f32 v164, v40, v57
	s_nop 0
	v_mov_b32_e32 v157, v3
	v_lshl_add_u64 v[2:3], s[18:19], 0, v[42:43]
	v_cvt_pk_bf16_f32 v165, v155, v157
	ds_read_b64_tr_b16 v[186:187], v89
	ds_read_b64_tr_b16 v[188:189], v90
	ds_read_b64_tr_b16 v[182:183], v91
	ds_read_b64_tr_b16 v[184:185], v92
	ds_read_b64_tr_b16 v[178:179], v93
	ds_read_b64_tr_b16 v[180:181], v94
	ds_read_b64_tr_b16 v[174:175], v95
	ds_read_b64_tr_b16 v[176:177], v96
	s_waitcnt lgkmcnt(0)
	v_lshl_add_u64 v[2:3], v[2:3], 0, v[44:45]
	ds_write_b64 v29, v[26:27]
	global_load_lds_dwordx4 v[2:3], off
	v_lshl_add_u64 v[2:3], s[22:23], 0, v[42:43]
	v_lshl_add_u64 v[2:3], v[2:3], 0, v[52:53]
	s_mov_b32 m0, s58
	v_lshlrev_b32_sdwa v42, v64, v4 dst_sel:DWORD dst_unused:UNUSED_PAD src0_sel:DWORD src1_sel:WORD_1
	global_load_lds_dwordx4 v[2:3], off
	v_lshl_add_u64 v[2:3], s[18:19], 0, v[42:43]
	v_lshl_add_u64 v[2:3], v[2:3], 0, v[50:51]
	s_mov_b32 m0, s59
	v_mfma_f32_16x16x32_bf16 v[166:169], v[162:165], v[178:181], v[166:169]
	global_load_lds_dwordx4 v[2:3], off
	v_lshl_add_u64 v[2:3], s[22:23], 0, v[42:43]
	v_lshl_add_u64 v[2:3], v[2:3], 0, v[52:53]
	s_mov_b32 m0, s60
	v_add_f32_e32 v27, v41, v57
	global_load_lds_dwordx4 v[2:3], off
	v_lshlrev_b32_e32 v2, 9, v5
	v_and_b32_e32 v42, 0x1fffe00, v2
	v_lshl_add_u64 v[2:3], s[18:19], 0, v[42:43]
	v_lshl_add_u64 v[2:3], v[2:3], 0, v[48:49]
	s_mov_b32 m0, s61
	v_mfma_f32_16x16x32_bf16 v[36:39], v[162:165], v[174:177], v[36:39]
	global_load_lds_dwordx4 v[2:3], off
	v_lshl_add_u64 v[2:3], s[22:23], 0, v[42:43]
	v_lshl_add_u64 v[2:3], v[2:3], 0, v[52:53]
	s_mov_b32 m0, s64
	v_lshlrev_b32_sdwa v42, v64, v5 dst_sel:DWORD dst_unused:UNUSED_PAD src0_sel:DWORD src1_sel:WORD_1
	global_load_lds_dwordx4 v[2:3], off
	v_lshl_add_u64 v[2:3], s[18:19], 0, v[42:43]
	v_lshl_add_u64 v[2:3], v[2:3], 0, v[46:47]
	s_mov_b32 m0, s65
	s_nop 0
	global_load_lds_dwordx4 v[2:3], off
	v_lshl_add_u64 v[2:3], s[22:23], 0, v[42:43]
	v_lshl_add_u64 v[2:3], v[2:3], 0, v[52:53]
	s_mov_b32 m0, s66
	s_nop 0
	global_load_lds_dwordx4 v[2:3], off
	v_mfma_f32_16x16x32_bf16 v[2:5], v[162:165], v[186:189], v[22:25]
	s_waitcnt vmcnt(8)
	s_nop 2
	v_add_f32_e32 v22, v31, v40
	v_add_f32_e32 v26, v30, v22
	v_mfma_f32_16x16x32_bf16 v[22:25], v[162:165], v[182:185], v[170:173]
	s_nop 2
	ds_read_b128 v[170:173], v145
	ds_read_b128 v[178:181], v149
	ds_read_b128 v[182:185], v151
	ds_read_b128 v[186:189], v153
	v_add_f32_e32 v26, v27, v26
	v_add_f32_e32 v27, v59, v155
	v_add_f32_e32 v26, v27, v26
	v_add_f32_e32 v27, v156, v157
	v_add_f32_e32 v29, v27, v26
	s_waitcnt lgkmcnt(0)
	v_mfma_f32_16x16x32_bf16 v[162:165], v[170:173], v[10:13], 0
	s_mov_b32 m0, s46
	v_mfma_f32_16x16x32_bf16 v[170:173], v[182:185], v[10:13], 0
	v_mfma_f32_16x16x32_bf16 v[162:165], v[178:181], v[6:9], v[162:165]
	v_mfma_f32_16x16x32_bf16 v[170:173], v[186:189], v[6:9], v[170:173]
	s_nop 6
	v_mul_f32_e32 v26, 0x3fb8aa3b, v162
	v_exp_f32_e32 v26, v26
	v_mul_f32_e32 v27, 0x3fb8aa3b, v170
	v_exp_f32_e32 v27, v27
	v_mov_b32_e32 v30, v26
	v_mul_f32_e32 v26, 0x3fb8aa3b, v163
	v_exp_f32_e32 v26, v26
	s_nop 0
	v_mov_b32_e32 v31, v27
	v_mul_f32_e32 v27, 0x3fb8aa3b, v171
	v_exp_f32_e32 v27, v27
	s_nop 1
	v_mov_b32_e32 v40, v26
	v_mul_f32_e32 v26, 0x3fb8aa3b, v164
	v_exp_f32_e32 v26, v26
	v_cvt_pk_bf16_f32 v162, v30, v40
	s_nop 0
	v_mov_b32_e32 v41, v27
	v_mul_f32_e32 v27, 0x3fb8aa3b, v172
	v_exp_f32_e32 v27, v27
	s_nop 1
	v_mov_b32_e32 v57, v26
	v_mul_f32_e32 v26, 0x3fb8aa3b, v165
	v_exp_f32_e32 v26, v26
	s_nop 0
	v_mov_b32_e32 v59, v27
	v_mul_f32_e32 v27, 0x3fb8aa3b, v173
	v_exp_f32_e32 v27, v27
	s_nop 1
	v_mov_b32_e32 v155, v26
	v_lshlrev_b32_e32 v26, 9, v32
	v_and_b32_e32 v42, 0x1fffe00, v26
	v_cvt_pk_bf16_f32 v163, v57, v155
	v_cvt_pk_bf16_f32 v164, v31, v41
	s_nop 0
	v_mov_b32_e32 v156, v27
	v_lshl_add_u64 v[26:27], s[18:19], 0, v[42:43]
	v_cvt_pk_bf16_f32 v165, v59, v156
	ds_read_b64_tr_b16 v[182:183], v73
	ds_read_b64_tr_b16 v[184:185], v74
	ds_read_b64_tr_b16 v[178:179], v75
	ds_read_b64_tr_b16 v[180:181], v76
	ds_read_b64_tr_b16 v[174:175], v77
	ds_read_b64_tr_b16 v[176:177], v78
	ds_read_b64_tr_b16 v[170:171], v79
	ds_read_b64_tr_b16 v[172:173], v80
	s_waitcnt lgkmcnt(0)
	v_lshl_add_u64 v[26:27], v[26:27], 0, v[44:45]
	global_load_lds_dwordx4 v[26:27], off
	v_lshl_add_u64 v[26:27], s[22:23], 0, v[42:43]
	v_lshl_add_u64 v[26:27], v[26:27], 0, v[52:53]
	s_mov_b32 m0, s48
	v_lshlrev_b32_sdwa v42, v64, v32 dst_sel:DWORD dst_unused:UNUSED_PAD src0_sel:DWORD src1_sel:WORD_1
	global_load_lds_dwordx4 v[26:27], off
	v_lshl_add_u64 v[26:27], s[18:19], 0, v[42:43]
	v_lshl_add_u64 v[26:27], v[26:27], 0, v[50:51]
	s_mov_b32 m0, s49
	v_mfma_f32_16x16x32_bf16 v[182:185], v[162:165], v[182:185], v[2:5]
	global_load_lds_dwordx4 v[26:27], off
	v_lshl_add_u64 v[26:27], s[22:23], 0, v[42:43]
	v_lshl_add_u64 v[26:27], v[26:27], 0, v[52:53]
	s_mov_b32 m0, s50
	v_add_f32_e32 v2, v30, v31
	global_load_lds_dwordx4 v[26:27], off
	v_lshlrev_b32_e32 v26, 9, v33
	v_and_b32_e32 v42, 0x1fffe00, v26
	v_lshl_add_u64 v[26:27], s[18:19], 0, v[42:43]
	v_lshl_add_u64 v[26:27], v[26:27], 0, v[48:49]
	s_mov_b32 m0, s51
	v_add_f32_e32 v2, v29, v2
	global_load_lds_dwordx4 v[26:27], off
	v_lshl_add_u64 v[26:27], s[22:23], 0, v[42:43]
	v_lshl_add_u64 v[26:27], v[26:27], 0, v[52:53]
	s_mov_b32 m0, s52
	v_lshlrev_b32_sdwa v42, v64, v33 dst_sel:DWORD dst_unused:UNUSED_PAD src0_sel:DWORD src1_sel:WORD_1
	global_load_lds_dwordx4 v[26:27], off
	v_lshl_add_u64 v[26:27], s[18:19], 0, v[42:43]
	v_lshl_add_u64 v[26:27], v[26:27], 0, v[46:47]
	s_mov_b32 m0, s53
	v_add_f32_e32 v3, v40, v41
	global_load_lds_dwordx4 v[26:27], off
	v_lshl_add_u64 v[26:27], s[22:23], 0, v[42:43]
	v_lshl_add_u64 v[26:27], v[26:27], 0, v[52:53]
	s_mov_b32 m0, s54
	v_add_f32_e32 v2, v3, v2
	global_load_lds_dwordx4 v[26:27], off
	v_add_f32_e32 v3, v57, v59
	s_waitcnt vmcnt(8)
	v_mfma_f32_16x16x32_bf16 v[178:181], v[162:165], v[178:181], v[22:25]
	v_add_f32_e32 v26, v3, v2
	v_add_f32_e32 v27, v155, v156
	v_add_f32_e32 v57, v27, v26
	v_mfma_f32_16x16x32_bf16 v[166:169], v[162:165], v[174:177], v[166:169]
	ds_read_b128 v[2:5], v145 offset:8192
	ds_read_b128 v[22:25], v149 offset:8192
	ds_read_b128 v[30:33], v151 offset:8192
	ds_read_b128 v[174:177], v153 offset:8192
	v_mfma_f32_16x16x32_bf16 v[36:39], v[162:165], v[170:173], v[36:39]
	s_waitcnt lgkmcnt(0)
	v_mfma_f32_16x16x32_bf16 v[2:5], v[2:5], v[10:13], 0
	v_lshlrev_b32_e32 v40, 9, v34
	v_and_b32_e32 v42, 0x1fffe00, v40
	v_mfma_f32_16x16x32_bf16 v[2:5], v[22:25], v[6:9], v[2:5]
	v_lshl_add_u64 v[40:41], s[18:19], 0, v[42:43]
	s_mov_b32 m0, s44
	v_lshl_add_u64 v[40:41], v[40:41], 0, v[44:45]
	v_mfma_f32_16x16x32_bf16 v[22:25], v[30:33], v[10:13], 0
	v_mfma_f32_16x16x32_bf16 v[22:25], v[174:177], v[6:9], v[22:25]
	s_nop 2
	v_mul_f32_e32 v2, 0x3fb8aa3b, v2
	v_exp_f32_e32 v2, v2
	s_nop 0
	v_mov_b32_e32 v59, v2
	v_mul_f32_e32 v2, 0x3fb8aa3b, v3
	v_mul_f32_e32 v22, 0x3fb8aa3b, v22
	v_exp_f32_e32 v22, v22
	v_exp_f32_e32 v2, v2
	v_mul_f32_e32 v3, 0x3fb8aa3b, v23
	v_exp_f32_e32 v3, v3
	s_nop 1
	v_mov_b32_e32 v155, v22
	s_nop 1
	v_mov_b32_e32 v156, v2
	v_mul_f32_e32 v2, 0x3fb8aa3b, v4
	v_exp_f32_e32 v2, v2
	v_mov_b32_e32 v157, v3
	v_mul_f32_e32 v3, 0x3fb8aa3b, v24
	v_exp_f32_e32 v3, v3
	v_cvt_pk_bf16_f32 v162, v59, v156
	s_nop 1
	v_mov_b32_e32 v158, v2
	v_mul_f32_e32 v2, 0x3fb8aa3b, v5
	v_exp_f32_e32 v2, v2
	v_mov_b32_e32 v160, v3
	v_mul_f32_e32 v3, 0x3fb8aa3b, v25
	v_exp_f32_e32 v3, v3
	s_nop 1
	v_mov_b32_e32 v198, v2
	v_cvt_pk_bf16_f32 v163, v158, v198
	v_cvt_pk_bf16_f32 v164, v155, v157
	s_nop 1
	v_mov_b32_e32 v199, v3
	v_cvt_pk_bf16_f32 v165, v160, v199
	ds_read_b64_tr_b16 v[190:191], v89
	ds_read_b64_tr_b16 v[192:193], v90
	ds_read_b64_tr_b16 v[186:187], v91
	ds_read_b64_tr_b16 v[188:189], v92
	ds_read_b64_tr_b16 v[174:175], v93
	ds_read_b64_tr_b16 v[176:177], v94
	ds_read_b64_tr_b16 v[170:171], v95
	ds_read_b64_tr_b16 v[172:173], v96
	s_waitcnt lgkmcnt(0)
	s_waitcnt lgkmcnt(0)
	ds_read_b128 v[30:33], v28
	ds_read_b128 v[22:25], v28 offset:16
	ds_read_b128 v[2:5], v28 offset:32
	ds_read_b128 v[26:29], v28 offset:48
	global_load_lds_dwordx4 v[40:41], off
	v_lshl_add_u64 v[40:41], s[22:23], 0, v[42:43]
	v_lshl_add_u64 v[40:41], v[40:41], 0, v[52:53]
	s_mov_b32 m0, s58
	v_lshlrev_b32_sdwa v42, v64, v34 dst_sel:DWORD dst_unused:UNUSED_PAD src0_sel:DWORD src1_sel:WORD_1
	global_load_lds_dwordx4 v[40:41], off
	v_lshl_add_u64 v[40:41], s[18:19], 0, v[42:43]
	v_lshl_add_u64 v[40:41], v[40:41], 0, v[50:51]
	s_mov_b32 m0, s59
	v_lshlrev_b32_e32 v34, 9, v35
	global_load_lds_dwordx4 v[40:41], off
	v_lshl_add_u64 v[40:41], s[22:23], 0, v[42:43]
	v_lshl_add_u64 v[40:41], v[40:41], 0, v[52:53]
	s_mov_b32 m0, s60
	v_and_b32_e32 v42, 0x1fffe00, v34
	global_load_lds_dwordx4 v[40:41], off
	v_lshl_add_u64 v[40:41], s[18:19], 0, v[42:43]
	v_lshl_add_u64 v[40:41], v[40:41], 0, v[48:49]
	s_mov_b32 m0, s61
	v_mfma_f32_16x16x32_bf16 v[182:185], v[162:165], v[190:193], v[182:185]
	global_load_lds_dwordx4 v[40:41], off
	v_lshl_add_u64 v[40:41], s[22:23], 0, v[42:43]
	v_lshlrev_b32_sdwa v42, v64, v35 dst_sel:DWORD dst_unused:UNUSED_PAD src0_sel:DWORD src1_sel:WORD_1
	v_lshl_add_u64 v[40:41], v[40:41], 0, v[52:53]
	s_mov_b32 m0, s64
	v_lshl_add_u64 v[34:35], s[18:19], 0, v[42:43]
	global_load_lds_dwordx4 v[40:41], off
	v_lshl_add_u64 v[34:35], v[34:35], 0, v[46:47]
	s_mov_b32 m0, s65
	v_mfma_f32_16x16x32_bf16 v[178:181], v[162:165], v[186:189], v[178:181]
	global_load_lds_dwordx4 v[34:35], off
	v_lshl_add_u64 v[34:35], s[22:23], 0, v[42:43]
	v_lshl_add_u64 v[34:35], v[34:35], 0, v[52:53]
	s_mov_b32 m0, s66
	v_mfma_f32_16x16x32_bf16 v[166:169], v[162:165], v[174:177], v[166:169]
	global_load_lds_dwordx4 v[34:35], off
	s_waitcnt vmcnt(8)
	v_add_f32_e32 v34, v59, v155
	ds_read_b128 v[174:177], v145
	ds_read_b128 v[186:189], v149
	ds_read_b128 v[190:193], v151
	ds_read_b128 v[194:197], v153
	v_add_f32_e32 v34, v57, v34
	v_add_f32_e32 v35, v156, v157
	v_add_f32_e32 v34, v35, v34
	v_add_f32_e32 v35, v158, v160
	v_add_f32_e32 v40, v35, v34
	v_mfma_f32_16x16x32_bf16 v[34:37], v[162:165], v[170:173], v[36:39]
	s_nop 2
	v_add_f32_e32 v38, v198, v199
	v_add_f32_e32 v57, v38, v40
	s_waitcnt lgkmcnt(0)
	v_mfma_f32_16x16x32_bf16 v[38:41], v[174:177], v[10:13], 0
	s_mov_b32 m0, s46
	v_mfma_f32_16x16x32_bf16 v[38:41], v[186:189], v[6:9], v[38:41]
	v_mfma_f32_16x16x32_bf16 v[162:165], v[190:193], v[10:13], 0
	v_mfma_f32_16x16x32_bf16 v[162:165], v[194:197], v[6:9], v[162:165]
	s_nop 5
	v_mul_f32_e32 v38, 0x3fb8aa3b, v38
	v_exp_f32_e32 v38, v38
	s_nop 0
	v_mov_b32_e32 v59, v38
	v_mul_f32_e32 v38, 0x3fb8aa3b, v39
	v_mul_f32_e32 v42, 0x3fb8aa3b, v162
	v_exp_f32_e32 v42, v42
	v_exp_f32_e32 v38, v38
	v_mul_f32_e32 v39, 0x3fb8aa3b, v163
	v_exp_f32_e32 v39, v39
	s_nop 1
	v_mov_b32_e32 v155, v42
	v_lshlrev_b32_e32 v42, 9, v30
	v_and_b32_e32 v42, 0x1fffe00, v42
	v_mov_b32_e32 v158, v38
	v_mul_f32_e32 v38, 0x3fb8aa3b, v40
	v_exp_f32_e32 v38, v38
	v_mov_b32_e32 v160, v39
	v_mul_f32_e32 v39, 0x3fb8aa3b, v164
	v_exp_f32_e32 v39, v39
	v_lshl_add_u64 v[156:157], s[14:15], 0, v[42:43]
	v_lshl_add_u64 v[156:157], v[156:157], 0, v[44:45]
	v_mov_b32_e32 v190, v38
	v_mul_f32_e32 v38, 0x3fb8aa3b, v41
	v_exp_f32_e32 v38, v38
	v_mov_b32_e32 v191, v39
	v_mul_f32_e32 v39, 0x3fb8aa3b, v165
	v_exp_f32_e32 v39, v39
	s_nop 1
	v_mov_b32_e32 v194, v38
	v_cvt_pk_bf16_f32 v38, v59, v158
	s_nop 1
	v_mov_b32_e32 v195, v39
	v_cvt_pk_bf16_f32 v39, v190, v194
	v_cvt_pk_bf16_f32 v40, v155, v160
	v_cvt_pk_bf16_f32 v41, v191, v195
	ds_read_b64_tr_b16 v[186:187], v73
	ds_read_b64_tr_b16 v[188:189], v74
	ds_read_b64_tr_b16 v[174:175], v75
	ds_read_b64_tr_b16 v[176:177], v76
	ds_read_b64_tr_b16 v[170:171], v77
	ds_read_b64_tr_b16 v[172:173], v78
	ds_read_b64_tr_b16 v[162:163], v79
	ds_read_b64_tr_b16 v[164:165], v80
	s_waitcnt lgkmcnt(0)
	global_load_lds_dwordx4 v[156:157], off
	v_lshl_add_u64 v[156:157], s[16:17], 0, v[42:43]
	v_lshl_add_u64 v[156:157], v[156:157], 0, v[52:53]
	s_mov_b32 m0, s48
	v_lshlrev_b32_sdwa v42, v64, v30 dst_sel:DWORD dst_unused:UNUSED_PAD src0_sel:DWORD src1_sel:WORD_1
	global_load_lds_dwordx4 v[156:157], off
	v_lshl_add_u64 v[156:157], s[14:15], 0, v[42:43]
	v_lshl_add_u64 v[156:157], v[156:157], 0, v[50:51]
	s_mov_b32 m0, s49
	v_lshlrev_b32_e32 v30, 9, v31
	global_load_lds_dwordx4 v[156:157], off
	v_lshl_add_u64 v[156:157], s[16:17], 0, v[42:43]
	v_lshl_add_u64 v[156:157], v[156:157], 0, v[52:53]
	s_mov_b32 m0, s50
	v_and_b32_e32 v42, 0x1fffe00, v30
	global_load_lds_dwordx4 v[156:157], off
	v_lshl_add_u64 v[156:157], s[14:15], 0, v[42:43]
	v_lshl_add_u64 v[156:157], v[156:157], 0, v[48:49]
	s_mov_b32 m0, s51
	v_mfma_f32_16x16x32_bf16 v[182:185], v[38:41], v[186:189], v[182:185]
	global_load_lds_dwordx4 v[156:157], off
	v_lshl_add_u64 v[156:157], s[16:17], 0, v[42:43]
	v_lshlrev_b32_sdwa v42, v64, v31 dst_sel:DWORD dst_unused:UNUSED_PAD src0_sel:DWORD src1_sel:WORD_1
	v_lshl_add_u64 v[156:157], v[156:157], 0, v[52:53]
	s_mov_b32 m0, s52
	v_lshl_add_u64 v[30:31], s[14:15], 0, v[42:43]
	global_load_lds_dwordx4 v[156:157], off
	v_lshl_add_u64 v[30:31], v[30:31], 0, v[46:47]
	s_mov_b32 m0, s53
	v_mfma_f32_16x16x32_bf16 v[174:177], v[38:41], v[174:177], v[178:181]
	global_load_lds_dwordx4 v[30:31], off
	v_lshl_add_u64 v[30:31], s[16:17], 0, v[42:43]
	v_lshl_add_u64 v[30:31], v[30:31], 0, v[52:53]
	s_mov_b32 m0, s54
	v_mfma_f32_16x16x32_bf16 v[166:169], v[38:41], v[170:173], v[166:169]
	global_load_lds_dwordx4 v[30:31], off
	v_add_f32_e32 v30, v59, v155
	v_add_f32_e32 v30, v57, v30
	v_add_f32_e32 v31, v158, v160
	s_waitcnt vmcnt(8)
	v_add_f32_e32 v30, v31, v30
	v_add_f32_e32 v31, v190, v191
	ds_read_b128 v[170:173], v145 offset:8192
	ds_read_b128 v[178:181], v149 offset:8192
	ds_read_b128 v[186:189], v151 offset:8192
	ds_read_b128 v[190:193], v153 offset:8192
	v_add_f32_e32 v30, v31, v30
	v_add_f32_e32 v31, v194, v195
	v_add_f32_e32 v30, v31, v30
	v_mfma_f32_16x16x32_bf16 v[162:165], v[38:41], v[162:165], v[34:37]
	s_waitcnt lgkmcnt(0)
	v_mfma_f32_16x16x32_bf16 v[34:37], v[170:173], v[10:13], 0
	v_mfma_f32_16x16x32_bf16 v[10:13], v[186:189], v[10:13], 0
	v_mfma_f32_16x16x32_bf16 v[34:37], v[178:181], v[6:9], v[34:37]
	v_mfma_f32_16x16x32_bf16 v[6:9], v[190:193], v[6:9], v[10:13]
	s_nop 6
	v_mul_f32_e32 v31, 0x3fb8aa3b, v34
	v_exp_f32_e32 v10, v31
	v_mul_f32_e32 v6, 0x3fb8aa3b, v6
	v_exp_f32_e32 v6, v6
	v_mul_f32_e32 v12, 0x3fb8aa3b, v35
	v_exp_f32_e32 v12, v12
	v_mul_f32_e32 v7, 0x3fb8aa3b, v7
	v_exp_f32_e32 v7, v7
	v_mul_f32_e32 v8, 0x3fb8aa3b, v8
	v_exp_f32_e32 v8, v8
	v_mov_b32_e32 v11, v6
	v_add_f32_e32 v6, v10, v11
	v_add_f32_e32 v6, v30, v6
	v_mov_b32_e32 v12, v12
	s_nop 1
	v_mov_b32_e32 v13, v7
	v_add_f32_e32 v7, v12, v13
	v_add_f32_e32 v6, v7, v6
	v_mul_f32_e32 v7, 0x3fb8aa3b, v36
	v_exp_f32_e32 v7, v7
	s_nop 1
	v_mov_b32_e32 v7, v7
	s_nop 1
	v_mov_b32_e32 v30, v8
	v_add_f32_e32 v8, v7, v30
	v_add_f32_e32 v31, v8, v6
	v_mul_f32_e32 v6, 0x3fb8aa3b, v37
	v_exp_f32_e32 v6, v6
	v_mul_f32_e32 v8, 0x3fb8aa3b, v9
	v_exp_f32_e32 v8, v8
	s_nop 1
	v_mov_b32_e32 v42, v6
	v_cvt_pk_bf16_f32 v6, v10, v12
	v_cvt_pk_bf16_f32 v7, v7, v42
	s_nop 1
	v_mov_b32_e32 v57, v8
	s_branch .Lg_join
.Lg_masked:
	v_cmp_ge_i32_e32 vcc, s13, v65
	s_mov_b32 m0, s46
	v_mfma_f32_16x16x32_bf16 v[36:39], v[162:165], v[6:9], v[36:39]
	v_mfma_f32_16x16x32_bf16 v[162:165], v[166:169], v[10:13], 0
	v_mfma_f32_16x16x32_bf16 v[162:165], v[170:173], v[6:9], v[162:165]
	s_nop 5
	v_mul_f32_e32 v30, 0x3fb8aa3b, v36
	v_exp_f32_e32 v30, v30
	s_nop 0
	v_cndmask_b32_e32 v40, 0, v30, vcc
	v_mul_f32_e32 v30, 0x3fb8aa3b, v37
	v_mul_f32_e32 v31, 0x3fb8aa3b, v162
	v_exp_f32_e32 v31, v31
	v_cmp_ge_i32_e32 vcc, s13, v66
	v_exp_f32_e32 v30, v30
	s_nop 0
	v_cndmask_b32_e32 v41, 0, v31, vcc
	v_mul_f32_e32 v31, 0x3fb8aa3b, v163
	v_exp_f32_e32 v31, v31
	v_cmp_ge_i32_e32 vcc, s13, v67
	s_nop 1
	v_cndmask_b32_e32 v57, 0, v30, vcc
	v_mul_f32_e32 v30, 0x3fb8aa3b, v38
	v_cmp_ge_i32_e32 vcc, s13, v68
	v_exp_f32_e32 v30, v30
	v_cvt_pk_bf16_f32 v36, v40, v57
	s_nop 0
	v_cndmask_b32_e32 v59, 0, v31, vcc
	v_mul_f32_e32 v31, 0x3fb8aa3b, v164
	v_exp_f32_e32 v31, v31
	v_cmp_ge_i32_e32 vcc, s13, v69
	s_nop 1
	v_cndmask_b32_e32 v155, 0, v30, vcc
	v_mul_f32_e32 v30, 0x3fb8aa3b, v39
	v_cmp_ge_i32_e32 vcc, s13, v70
	v_exp_f32_e32 v30, v30
	s_nop 0
	v_cndmask_b32_e32 v156, 0, v31, vcc
	v_mul_f32_e32 v31, 0x3fb8aa3b, v165
	v_exp_f32_e32 v31, v31
	v_cmp_ge_i32_e32 vcc, s13, v71
	s_nop 1
	v_cndmask_b32_e32 v157, 0, v30, vcc
	v_lshlrev_b32_e32 v30, 9, v22
	v_cmp_ge_i32_e32 vcc, s13, v72
	v_and_b32_e32 v42, 0x1fffe00, v30
	v_cvt_pk_bf16_f32 v37, v155, v157
	v_cvt_pk_bf16_f32 v38, v41, v59
	s_nop 0
	v_cndmask_b32_e32 v158, 0, v31, vcc
	v_lshl_add_u64 v[30:31], s[18:19], 0, v[42:43]
	v_cvt_pk_bf16_f32 v39, v156, v158
	ds_read_b64_tr_b16 v[174:175], v73
	ds_read_b64_tr_b16 v[176:177], v74
	ds_read_b64_tr_b16 v[170:171], v75
	ds_read_b64_tr_b16 v[172:173], v76
	ds_read_b64_tr_b16 v[166:167], v77
	ds_read_b64_tr_b16 v[168:169], v78
	ds_read_b64_tr_b16 v[162:163], v79
	ds_read_b64_tr_b16 v[164:165], v80
	s_waitcnt lgkmcnt(0)
	v_lshl_add_u64 v[30:31], v[30:31], 0, v[44:45]
	global_load_lds_dwordx4 v[30:31], off
	v_lshl_add_u64 v[30:31], s[22:23], 0, v[42:43]
	v_lshl_add_u64 v[30:31], v[30:31], 0, v[52:53]
	s_mov_b32 m0, s48
	v_lshlrev_b32_sdwa v42, v64, v22 dst_sel:DWORD dst_unused:UNUSED_PAD src0_sel:DWORD src1_sel:WORD_1
	global_load_lds_dwordx4 v[30:31], off
	v_lshl_add_u64 v[30:31], s[18:19], 0, v[42:43]
	v_lshl_add_u64 v[30:31], v[30:31], 0, v[50:51]
	s_mov_b32 m0, s49
	v_lshlrev_b32_e32 v22, 9, v23
	global_load_lds_dwordx4 v[30:31], off
	v_lshl_add_u64 v[30:31], s[22:23], 0, v[42:43]
	v_lshl_add_u64 v[30:31], v[30:31], 0, v[52:53]
	s_mov_b32 m0, s50
	v_and_b32_e32 v42, 0x1fffe00, v22
	global_load_lds_dwordx4 v[30:31], off
	v_lshl_add_u64 v[30:31], s[18:19], 0, v[42:43]
	v_lshl_add_u64 v[30:31], v[30:31], 0, v[48:49]
	s_mov_b32 m0, s51
	v_mfma_f32_16x16x32_bf16 v[174:177], v[36:39], v[174:177], 0
	global_load_lds_dwordx4 v[30:31], off
	v_lshl_add_u64 v[30:31], s[22:23], 0, v[42:43]
	v_lshlrev_b32_sdwa v42, v64, v23 dst_sel:DWORD dst_unused:UNUSED_PAD src0_sel:DWORD src1_sel:WORD_1
	v_lshl_add_u64 v[30:31], v[30:31], 0, v[52:53]
	s_mov_b32 m0, s52
	v_lshl_add_u64 v[22:23], s[18:19], 0, v[42:43]
	global_load_lds_dwordx4 v[30:31], off
	v_lshl_add_u64 v[22:23], v[22:23], 0, v[46:47]
	s_mov_b32 m0, s53
	v_mfma_f32_16x16x32_bf16 v[170:173], v[36:39], v[170:173], 0
	global_load_lds_dwordx4 v[22:23], off
	v_lshl_add_u64 v[22:23], s[22:23], 0, v[42:43]
	v_lshl_add_u64 v[22:23], v[22:23], 0, v[52:53]
	s_mov_b32 m0, s54
	v_mfma_f32_16x16x32_bf16 v[166:169], v[36:39], v[166:169], 0
	global_load_lds_dwordx4 v[22:23], off
	s_waitcnt vmcnt(8)
	ds_read_b128 v[178:181], v145 offset:8192
	ds_read_b128 v[182:185], v149 offset:8192
	ds_read_b128 v[186:189], v151 offset:8192
	ds_read_b128 v[190:193], v153 offset:8192
	v_add_f32_e32 v22, v40, v41
	v_add_f32_e32 v22, 0, v22
	v_add_f32_e32 v23, v57, v59
	v_mfma_f32_16x16x32_bf16 v[36:39], v[36:39], v[162:165], 0
	v_add_f32_e32 v22, v23, v22
	v_add_f32_e32 v23, v155, v156
	v_add_f32_e32 v22, v23, v22
	v_add_f32_e32 v23, v157, v158
	v_add_f32_e32 v30, v23, v22
	s_waitcnt lgkmcnt(0)
	v_mfma_f32_16x16x32_bf16 v[162:165], v[178:181], v[10:13], 0
	v_cmp_ge_i32_e32 vcc, s13, v81
	s_mov_b32 m0, s44
	v_mfma_f32_16x16x32_bf16 v[178:181], v[186:189], v[10:13], 0
	v_mfma_f32_16x16x32_bf16 v[162:165], v[182:185], v[6:9], v[162:165]
	v_mfma_f32_16x16x32_bf16 v[178:181], v[190:193], v[6:9], v[178:181]
	s_nop 6
	v_mul_f32_e32 v22, 0x3fb8aa3b, v162
	v_exp_f32_e32 v22, v22
	v_mul_f32_e32 v23, 0x3fb8aa3b, v178
	v_exp_f32_e32 v23, v23
	v_cndmask_b32_e32 v31, 0, v22, vcc
	v_mul_f32_e32 v22, 0x3fb8aa3b, v163
	v_cmp_ge_i32_e32 vcc, s13, v82
	v_exp_f32_e32 v22, v22
	s_nop 0
	v_cndmask_b32_e32 v40, 0, v23, vcc
	v_mul_f32_e32 v23, 0x3fb8aa3b, v179
	v_exp_f32_e32 v23, v23
	v_cmp_ge_i32_e32 vcc, s13, v83
	s_nop 1
	v_cndmask_b32_e32 v41, 0, v22, vcc
	v_mul_f32_e32 v22, 0x3fb8aa3b, v164
	v_cmp_ge_i32_e32 vcc, s13, v84
	v_exp_f32_e32 v22, v22
	v_cvt_pk_bf16_f32 v162, v31, v41
	v_add_f32_e32 v31, v31, v40
	v_cndmask_b32_e32 v57, 0, v23, vcc
	v_mul_f32_e32 v23, 0x3fb8aa3b, v180
	v_exp_f32_e32 v23, v23
	v_cmp_ge_i32_e32 vcc, s13, v85
	v_add_f32_e32 v30, v30, v31
	v_add_f32_e32 v31, v41, v57
	v_cndmask_b32_e32 v59, 0, v22, vcc
	v_mul_f32_e32 v22, 0x3fb8aa3b, v165
	v_cmp_ge_i32_e32 vcc, s13, v86
	v_exp_f32_e32 v22, v22
	v_add_f32_e32 v30, v31, v30
	v_cndmask_b32_e32 v155, 0, v23, vcc
	v_mul_f32_e32 v23, 0x3fb8aa3b, v181
	v_exp_f32_e32 v23, v23
	v_cmp_ge_i32_e32 vcc, s13, v87
	v_add_f32_e32 v31, v59, v155
	v_add_f32_e32 v30, v31, v30
	v_cndmask_b32_e32 v156, 0, v22, vcc
	v_lshlrev_b32_e32 v22, 9, v24
	v_cmp_ge_i32_e32 vcc, s13, v88
	v_and_b32_e32 v42, 0x1fffe00, v22
	v_cvt_pk_bf16_f32 v163, v59, v156
	v_cvt_pk_bf16_f32 v164, v40, v57
	s_nop 0
	v_cndmask_b32_e32 v157, 0, v23, vcc
	v_lshl_add_u64 v[22:23], s[18:19], 0, v[42:43]
	v_cvt_pk_bf16_f32 v165, v155, v157
	ds_read_b64_tr_b16 v[190:191], v89
	ds_read_b64_tr_b16 v[192:193], v90
	ds_read_b64_tr_b16 v[186:187], v91
	ds_read_b64_tr_b16 v[188:189], v92
	ds_read_b64_tr_b16 v[182:183], v93
	ds_read_b64_tr_b16 v[184:185], v94
	ds_read_b64_tr_b16 v[178:179], v95
	ds_read_b64_tr_b16 v[180:181], v96
	s_waitcnt lgkmcnt(0)
	v_lshl_add_u64 v[22:23], v[22:23], 0, v[44:45]
	global_load_lds_dwordx4 v[22:23], off
	v_lshl_add_u64 v[22:23], s[22:23], 0, v[42:43]
	v_lshl_add_u64 v[22:23], v[22:23], 0, v[52:53]
	s_mov_b32 m0, s58
	v_lshlrev_b32_sdwa v42, v64, v24 dst_sel:DWORD dst_unused:UNUSED_PAD src0_sel:DWORD src1_sel:WORD_1
	global_load_lds_dwordx4 v[22:23], off
	v_lshl_add_u64 v[22:23], s[18:19], 0, v[42:43]
	v_lshl_add_u64 v[22:23], v[22:23], 0, v[50:51]
	s_mov_b32 m0, s59
	v_mfma_f32_16x16x32_bf16 v[170:173], v[162:165], v[186:189], v[170:173]
	global_load_lds_dwordx4 v[22:23], off
	v_lshl_add_u64 v[22:23], s[22:23], 0, v[42:43]
	v_lshl_add_u64 v[22:23], v[22:23], 0, v[52:53]
	s_mov_b32 m0, s60
	v_mfma_f32_16x16x32_bf16 v[166:169], v[162:165], v[182:185], v[166:169]
	global_load_lds_dwordx4 v[22:23], off
	v_lshlrev_b32_e32 v22, 9, v25
	v_and_b32_e32 v42, 0x1fffe00, v22
	v_lshl_add_u64 v[22:23], s[18:19], 0, v[42:43]
	v_lshl_add_u64 v[22:23], v[22:23], 0, v[48:49]
	s_mov_b32 m0, s61
	v_mfma_f32_16x16x32_bf16 v[36:39], v[162:165], v[178:181], v[36:39]
	global_load_lds_dwordx4 v[22:23], off
	v_lshl_add_u64 v[22:23], s[22:23], 0, v[42:43]
	v_lshl_add_u64 v[22:23], v[22:23], 0, v[52:53]
	s_mov_b32 m0, s64
	v_lshlrev_b32_sdwa v42, v64, v25 dst_sel:DWORD dst_unused:UNUSED_PAD src0_sel:DWORD src1_sel:WORD_1
	global_load_lds_dwordx4 v[22:23], off
	v_lshl_add_u64 v[22:23], s[18:19], 0, v[42:43]
	v_lshl_add_u64 v[22:23], v[22:23], 0, v[46:47]
	s_mov_b32 m0, s65
	v_add_f32_e32 v31, v156, v157
	global_load_lds_dwordx4 v[22:23], off
	v_lshl_add_u64 v[22:23], s[22:23], 0, v[42:43]
	v_lshl_add_u64 v[22:23], v[22:23], 0, v[52:53]
	s_mov_b32 m0, s66
	v_add_f32_e32 v40, v31, v30
	global_load_lds_dwordx4 v[22:23], off
	s_waitcnt vmcnt(8)
	v_mfma_f32_16x16x32_bf16 v[22:25], v[162:165], v[190:193], v[174:177]
	s_nop 2
	ds_read_b128 v[174:177], v145
	ds_read_b128 v[182:185], v149
	ds_read_b128 v[186:189], v151
	ds_read_b128 v[190:193], v153
	s_waitcnt lgkmcnt(0)
	v_mfma_f32_16x16x32_bf16 v[162:165], v[174:177], v[10:13], 0
	v_cmp_ge_i32_e32 vcc, s13, v97
	s_mov_b32 m0, s46
	v_mfma_f32_16x16x32_bf16 v[174:177], v[186:189], v[10:13], 0
	v_mfma_f32_16x16x32_bf16 v[162:165], v[182:185], v[6:9], v[162:165]
	v_mfma_f32_16x16x32_bf16 v[174:177], v[190:193], v[6:9], v[174:177]
	s_nop 6
	v_mul_f32_e32 v30, 0x3fb8aa3b, v162
	v_exp_f32_e32 v30, v30
	v_mul_f32_e32 v31, 0x3fb8aa3b, v174
	v_exp_f32_e32 v31, v31
	v_cndmask_b32_e32 v41, 0, v30, vcc
	v_mul_f32_e32 v30, 0x3fb8aa3b, v163
	v_cmp_ge_i32_e32 vcc, s13, v98
	v_exp_f32_e32 v30, v30
	s_nop 0
	v_cndmask_b32_e32 v57, 0, v31, vcc
	v_mul_f32_e32 v31, 0x3fb8aa3b, v175
	v_exp_f32_e32 v31, v31
	v_cmp_ge_i32_e32 vcc, s13, v99
	s_nop 1
	v_cndmask_b32_e32 v59, 0, v30, vcc
	v_mul_f32_e32 v30, 0x3fb8aa3b, v164
	v_cmp_ge_i32_e32 vcc, s13, v100
	v_exp_f32_e32 v30, v30
	v_cvt_pk_bf16_f32 v162, v41, v59
	s_nop 0
	v_cndmask_b32_e32 v155, 0, v31, vcc
	v_mul_f32_e32 v31, 0x3fb8aa3b, v176
	v_exp_f32_e32 v31, v31
	v_cmp_ge_i32_e32 vcc, s13, v101
	s_nop 1
	v_cndmask_b32_e32 v156, 0, v30, vcc
	v_mul_f32_e32 v30, 0x3fb8aa3b, v165
	v_cmp_ge_i32_e32 vcc, s13, v102
	v_exp_f32_e32 v30, v30
	s_nop 0
	v_cndmask_b32_e32 v157, 0, v31, vcc
	v_mul_f32_e32 v31, 0x3fb8aa3b, v177
	v_exp_f32_e32 v31, v31
	v_cmp_ge_i32_e32 vcc, s13, v103
	s_nop 1
	v_cndmask_b32_e32 v158, 0, v30, vcc
	v_lshlrev_b32_e32 v30, 9, v2
	v_cmp_ge_i32_e32 vcc, s13, v104
	v_and_b32_e32 v42, 0x1fffe00, v30
	v_cvt_pk_bf16_f32 v163, v156, v158
	v_cvt_pk_bf16_f32 v164, v57, v155
	s_nop 0
	v_cndmask_b32_e32 v160, 0, v31, vcc
	v_lshl_add_u64 v[30:31], s[18:19], 0, v[42:43]
	v_cvt_pk_bf16_f32 v165, v157, v160
	ds_read_b64_tr_b16 v[186:187], v73
	ds_read_b64_tr_b16 v[188:189], v74
	ds_read_b64_tr_b16 v[182:183], v75
	ds_read_b64_tr_b16 v[184:185], v76
	ds_read_b64_tr_b16 v[178:179], v77
	ds_read_b64_tr_b16 v[180:181], v78
	ds_read_b64_tr_b16 v[174:175], v79
	ds_read_b64_tr_b16 v[176:177], v80
	s_waitcnt lgkmcnt(0)
	v_lshl_add_u64 v[30:31], v[30:31], 0, v[44:45]
	global_load_lds_dwordx4 v[30:31], off
	v_lshl_add_u64 v[30:31], s[22:23], 0, v[42:43]
	v_lshl_add_u64 v[30:31], v[30:31], 0, v[52:53]
	s_mov_b32 m0, s48
	v_lshlrev_b32_sdwa v42, v64, v2 dst_sel:DWORD dst_unused:UNUSED_PAD src0_sel:DWORD src1_sel:WORD_1
	global_load_lds_dwordx4 v[30:31], off
	v_lshl_add_u64 v[30:31], s[18:19], 0, v[42:43]
	v_lshl_add_u64 v[30:31], v[30:31], 0, v[50:51]
	s_mov_b32 m0, s49
	v_lshlrev_b32_e32 v2, 9, v3
	global_load_lds_dwordx4 v[30:31], off
	v_lshl_add_u64 v[30:31], s[22:23], 0, v[42:43]
	v_lshl_add_u64 v[30:31], v[30:31], 0, v[52:53]
	s_mov_b32 m0, s50
	v_and_b32_e32 v42, 0x1fffe00, v2
	global_load_lds_dwordx4 v[30:31], off
	v_lshl_add_u64 v[30:31], s[18:19], 0, v[42:43]
	v_lshl_add_u64 v[30:31], v[30:31], 0, v[48:49]
	s_mov_b32 m0, s51
	v_mfma_f32_16x16x32_bf16 v[22:25], v[162:165], v[186:189], v[22:25]
	global_load_lds_dwordx4 v[30:31], off
	v_lshl_add_u64 v[30:31], s[22:23], 0, v[42:43]
	v_lshlrev_b32_sdwa v42, v64, v3 dst_sel:DWORD dst_unused:UNUSED_PAD src0_sel:DWORD src1_sel:WORD_1
	v_lshl_add_u64 v[30:31], v[30:31], 0, v[52:53]
	s_mov_b32 m0, s52
	v_lshl_add_u64 v[2:3], s[18:19], 0, v[42:43]
	global_load_lds_dwordx4 v[30:31], off
	v_lshl_add_u64 v[2:3], v[2:3], 0, v[46:47]
	s_mov_b32 m0, s53
	v_mfma_f32_16x16x32_bf16 v[170:173], v[162:165], v[182:185], v[170:173]
	global_load_lds_dwordx4 v[2:3], off
	v_lshl_add_u64 v[2:3], s[22:23], 0, v[42:43]
	v_lshl_add_u64 v[2:3], v[2:3], 0, v[52:53]
	s_mov_b32 m0, s54
	v_mfma_f32_16x16x32_bf16 v[166:169], v[162:165], v[178:181], v[166:169]
	global_load_lds_dwordx4 v[2:3], off
	s_waitcnt vmcnt(8)
	ds_read_b128 v[178:181], v145 offset:8192
	ds_read_b128 v[182:185], v149 offset:8192
	ds_read_b128 v[186:189], v151 offset:8192
	ds_read_b128 v[190:193], v153 offset:8192
	v_add_f32_e32 v2, v41, v57
	v_add_f32_e32 v2, v40, v2
	v_add_f32_e32 v3, v59, v155
	v_mfma_f32_16x16x32_bf16 v[36:39], v[162:165], v[174:177], v[36:39]
	v_add_f32_e32 v2, v3, v2
	v_add_f32_e32 v3, v156, v157
	v_add_f32_e32 v2, v3, v2
	v_add_f32_e32 v3, v158, v160
	v_add_f32_e32 v30, v3, v2
	s_waitcnt lgkmcnt(0)
	v_mfma_f32_16x16x32_bf16 v[162:165], v[178:181], v[10:13], 0
	v_cmp_ge_i32_e32 vcc, s13, v105
	s_mov_b32 m0, s44
	v_mfma_f32_16x16x32_bf16 v[174:177], v[186:189], v[10:13], 0
	v_mfma_f32_16x16x32_bf16 v[162:165], v[182:185], v[6:9], v[162:165]
	v_mfma_f32_16x16x32_bf16 v[174:177], v[190:193], v[6:9], v[174:177]
	s_nop 6
	v_mul_f32_e32 v2, 0x3fb8aa3b, v162
	v_exp_f32_e32 v2, v2
	v_mul_f32_e32 v3, 0x3fb8aa3b, v174
	v_exp_f32_e32 v3, v3
	v_cndmask_b32_e32 v31, 0, v2, vcc
	v_mul_f32_e32 v2, 0x3fb8aa3b, v163
	v_cmp_ge_i32_e32 vcc, s13, v106
	v_exp_f32_e32 v2, v2
	s_nop 0
	v_cndmask_b32_e32 v40, 0, v3, vcc
	v_mul_f32_e32 v3, 0x3fb8aa3b, v175
	v_exp_f32_e32 v3, v3
	v_cmp_ge_i32_e32 vcc, s13, v107
	s_nop 1
	v_cndmask_b32_e32 v41, 0, v2, vcc
	v_mul_f32_e32 v2, 0x3fb8aa3b, v164
	v_cmp_ge_i32_e32 vcc, s13, v108
	v_exp_f32_e32 v2, v2
	v_cvt_pk_bf16_f32 v162, v31, v41
	s_nop 0
	v_cndmask_b32_e32 v57, 0, v3, vcc
	v_mul_f32_e32 v3, 0x3fb8aa3b, v176
	v_exp_f32_e32 v3, v3
	v_cmp_ge_i32_e32 vcc, s13, v109
	s_nop 1
	v_cndmask_b32_e32 v59, 0, v2, vcc
	v_mul_f32_e32 v2, 0x3fb8aa3b, v165
	v_cmp_ge_i32_e32 vcc, s13, v110
	v_exp_f32_e32 v2, v2
	s_nop 0
	v_cndmask_b32_e32 v155, 0, v3, vcc
	v_mul_f32_e32 v3, 0x3fb8aa3b, v177
	v_exp_f32_e32 v3, v3
	v_cmp_ge_i32_e32 vcc, s13, v111
	s_nop 1
	v_cndmask_b32_e32 v156, 0, v2, vcc
	v_lshlrev_b32_e32 v2, 9, v4
	v_cmp_ge_i32_e32 vcc, s13, v112
	v_and_b32_e32 v42, 0x1fffe00, v2
	v_cvt_pk_bf16_f32 v163, v59, v156
	v_cvt_pk_bf16_f32 v164, v40, v57
	s_nop 0
	v_cndmask_b32_e32 v157, 0, v3, vcc
	v_lshl_add_u64 v[2:3], s[18:19], 0, v[42:43]
	v_cvt_pk_bf16_f32 v165, v155, v157
	ds_read_b64_tr_b16 v[186:187], v89
	ds_read_b64_tr_b16 v[188:189], v90
	ds_read_b64_tr_b16 v[182:183], v91
	ds_read_b64_tr_b16 v[184:185], v92
	ds_read_b64_tr_b16 v[178:179], v93
	ds_read_b64_tr_b16 v[180:181], v94
	ds_read_b64_tr_b16 v[174:175], v95
	ds_read_b64_tr_b16 v[176:177], v96
	s_waitcnt lgkmcnt(0)
	v_lshl_add_u64 v[2:3], v[2:3], 0, v[44:45]
	ds_write_b64 v29, v[26:27]
	global_load_lds_dwordx4 v[2:3], off
	v_lshl_add_u64 v[2:3], s[22:23], 0, v[42:43]
	v_lshl_add_u64 v[2:3], v[2:3], 0, v[52:53]
	s_mov_b32 m0, s58
	v_lshlrev_b32_sdwa v42, v64, v4 dst_sel:DWORD dst_unused:UNUSED_PAD src0_sel:DWORD src1_sel:WORD_1
	global_load_lds_dwordx4 v[2:3], off
	v_lshl_add_u64 v[2:3], s[18:19], 0, v[42:43]
	v_lshl_add_u64 v[2:3], v[2:3], 0, v[50:51]
	s_mov_b32 m0, s59
	v_mfma_f32_16x16x32_bf16 v[166:169], v[162:165], v[178:181], v[166:169]
	global_load_lds_dwordx4 v[2:3], off
	v_lshl_add_u64 v[2:3], s[22:23], 0, v[42:43]
	v_lshl_add_u64 v[2:3], v[2:3], 0, v[52:53]
	s_mov_b32 m0, s60
	v_add_f32_e32 v27, v41, v57
	global_load_lds_dwordx4 v[2:3], off
	v_lshlrev_b32_e32 v2, 9, v5
	v_and_b32_e32 v42, 0x1fffe00, v2
	v_lshl_add_u64 v[2:3], s[18:19], 0, v[42:43]
	v_lshl_add_u64 v[2:3], v[2:3], 0, v[48:49]
	s_mov_b32 m0, s61
	v_mfma_f32_16x16x32_bf16 v[36:39], v[162:165], v[174:177], v[36:39]
	global_load_lds_dwordx4 v[2:3], off
	v_lshl_add_u64 v[2:3], s[22:23], 0, v[42:43]
	v_lshl_add_u64 v[2:3], v[2:3], 0, v[52:53]
	s_mov_b32 m0, s64
	v_lshlrev_b32_sdwa v42, v64, v5 dst_sel:DWORD dst_unused:UNUSED_PAD src0_sel:DWORD src1_sel:WORD_1
	global_load_lds_dwordx4 v[2:3], off
	v_lshl_add_u64 v[2:3], s[18:19], 0, v[42:43]
	v_lshl_add_u64 v[2:3], v[2:3], 0, v[46:47]
	s_mov_b32 m0, s65
	s_nop 0
	global_load_lds_dwordx4 v[2:3], off
	v_lshl_add_u64 v[2:3], s[22:23], 0, v[42:43]
	v_lshl_add_u64 v[2:3], v[2:3], 0, v[52:53]
	s_mov_b32 m0, s66
	s_nop 0
	global_load_lds_dwordx4 v[2:3], off
	v_mfma_f32_16x16x32_bf16 v[2:5], v[162:165], v[186:189], v[22:25]
	s_waitcnt vmcnt(8)
	s_nop 2
	v_add_f32_e32 v22, v31, v40
	v_add_f32_e32 v26, v30, v22
	v_mfma_f32_16x16x32_bf16 v[22:25], v[162:165], v[182:185], v[170:173]
	s_nop 2
	ds_read_b128 v[170:173], v145
	ds_read_b128 v[178:181], v149
	ds_read_b128 v[182:185], v151
	ds_read_b128 v[186:189], v153
	v_add_f32_e32 v26, v27, v26
	v_add_f32_e32 v27, v59, v155
	v_add_f32_e32 v26, v27, v26
	v_add_f32_e32 v27, v156, v157
	v_add_f32_e32 v29, v27, v26
	s_waitcnt lgkmcnt(0)
	v_mfma_f32_16x16x32_bf16 v[162:165], v[170:173], v[10:13], 0
	v_cmp_ge_i32_e32 vcc, s13, v113
	s_mov_b32 m0, s46
	v_mfma_f32_16x16x32_bf16 v[170:173], v[182:185], v[10:13], 0
	v_mfma_f32_16x16x32_bf16 v[162:165], v[178:181], v[6:9], v[162:165]
	v_mfma_f32_16x16x32_bf16 v[170:173], v[186:189], v[6:9], v[170:173]
	s_nop 6
	v_mul_f32_e32 v26, 0x3fb8aa3b, v162
	v_exp_f32_e32 v26, v26
	v_mul_f32_e32 v27, 0x3fb8aa3b, v170
	v_exp_f32_e32 v27, v27
	v_cndmask_b32_e32 v30, 0, v26, vcc
	v_mul_f32_e32 v26, 0x3fb8aa3b, v163
	v_cmp_ge_i32_e32 vcc, s13, v114
	v_exp_f32_e32 v26, v26
	s_nop 0
	v_cndmask_b32_e32 v31, 0, v27, vcc
	v_mul_f32_e32 v27, 0x3fb8aa3b, v171
	v_exp_f32_e32 v27, v27
	v_cmp_ge_i32_e32 vcc, s13, v115
	s_nop 1
	v_cndmask_b32_e32 v40, 0, v26, vcc
	v_mul_f32_e32 v26, 0x3fb8aa3b, v164
	v_cmp_ge_i32_e32 vcc, s13, v116
	v_exp_f32_e32 v26, v26
	v_cvt_pk_bf16_f32 v162, v30, v40
	s_nop 0
	v_cndmask_b32_e32 v41, 0, v27, vcc
	v_mul_f32_e32 v27, 0x3fb8aa3b, v172
	v_exp_f32_e32 v27, v27
	v_cmp_ge_i32_e32 vcc, s13, v117
	s_nop 1
	v_cndmask_b32_e32 v57, 0, v26, vcc
	v_mul_f32_e32 v26, 0x3fb8aa3b, v165
	v_cmp_ge_i32_e32 vcc, s13, v118
	v_exp_f32_e32 v26, v26
	s_nop 0
	v_cndmask_b32_e32 v59, 0, v27, vcc
	v_mul_f32_e32 v27, 0x3fb8aa3b, v173
	v_exp_f32_e32 v27, v27
	v_cmp_ge_i32_e32 vcc, s13, v119
	s_nop 1
	v_cndmask_b32_e32 v155, 0, v26, vcc
	v_lshlrev_b32_e32 v26, 9, v32
	v_cmp_ge_i32_e32 vcc, s13, v120
	v_and_b32_e32 v42, 0x1fffe00, v26
	v_cvt_pk_bf16_f32 v163, v57, v155
	v_cvt_pk_bf16_f32 v164, v31, v41
	s_nop 0
	v_cndmask_b32_e32 v156, 0, v27, vcc
	v_lshl_add_u64 v[26:27], s[18:19], 0, v[42:43]
	v_cvt_pk_bf16_f32 v165, v59, v156
	ds_read_b64_tr_b16 v[182:183], v73
	ds_read_b64_tr_b16 v[184:185], v74
	ds_read_b64_tr_b16 v[178:179], v75
	ds_read_b64_tr_b16 v[180:181], v76
	ds_read_b64_tr_b16 v[174:175], v77
	ds_read_b64_tr_b16 v[176:177], v78
	ds_read_b64_tr_b16 v[170:171], v79
	ds_read_b64_tr_b16 v[172:173], v80
	s_waitcnt lgkmcnt(0)
	v_lshl_add_u64 v[26:27], v[26:27], 0, v[44:45]
	global_load_lds_dwordx4 v[26:27], off
	v_lshl_add_u64 v[26:27], s[22:23], 0, v[42:43]
	v_lshl_add_u64 v[26:27], v[26:27], 0, v[52:53]
	s_mov_b32 m0, s48
	v_lshlrev_b32_sdwa v42, v64, v32 dst_sel:DWORD dst_unused:UNUSED_PAD src0_sel:DWORD src1_sel:WORD_1
	global_load_lds_dwordx4 v[26:27], off
	v_lshl_add_u64 v[26:27], s[18:19], 0, v[42:43]
	v_lshl_add_u64 v[26:27], v[26:27], 0, v[50:51]
	s_mov_b32 m0, s49
	v_mfma_f32_16x16x32_bf16 v[182:185], v[162:165], v[182:185], v[2:5]
	global_load_lds_dwordx4 v[26:27], off
	v_lshl_add_u64 v[26:27], s[22:23], 0, v[42:43]
	v_lshl_add_u64 v[26:27], v[26:27], 0, v[52:53]
	s_mov_b32 m0, s50
	v_add_f32_e32 v2, v30, v31
	global_load_lds_dwordx4 v[26:27], off
	v_lshlrev_b32_e32 v26, 9, v33
	v_and_b32_e32 v42, 0x1fffe00, v26
	v_lshl_add_u64 v[26:27], s[18:19], 0, v[42:43]
	v_lshl_add_u64 v[26:27], v[26:27], 0, v[48:49]
	s_mov_b32 m0, s51
	v_add_f32_e32 v2, v29, v2
	global_load_lds_dwordx4 v[26:27], off
	v_lshl_add_u64 v[26:27], s[22:23], 0, v[42:43]
	v_lshl_add_u64 v[26:27], v[26:27], 0, v[52:53]
	s_mov_b32 m0, s52
	v_lshlrev_b32_sdwa v42, v64, v33 dst_sel:DWORD dst_unused:UNUSED_PAD src0_sel:DWORD src1_sel:WORD_1
	global_load_lds_dwordx4 v[26:27], off
	v_lshl_add_u64 v[26:27], s[18:19], 0, v[42:43]
	v_lshl_add_u64 v[26:27], v[26:27], 0, v[46:47]
	s_mov_b32 m0, s53
	v_add_f32_e32 v3, v40, v41
	global_load_lds_dwordx4 v[26:27], off
	v_lshl_add_u64 v[26:27], s[22:23], 0, v[42:43]
	v_lshl_add_u64 v[26:27], v[26:27], 0, v[52:53]
	s_mov_b32 m0, s54
	v_add_f32_e32 v2, v3, v2
	global_load_lds_dwordx4 v[26:27], off
	v_add_f32_e32 v3, v57, v59
	s_waitcnt vmcnt(8)
	v_mfma_f32_16x16x32_bf16 v[178:181], v[162:165], v[178:181], v[22:25]
	v_add_f32_e32 v26, v3, v2
	v_add_f32_e32 v27, v155, v156
	v_add_f32_e32 v57, v27, v26
	v_mfma_f32_16x16x32_bf16 v[166:169], v[162:165], v[174:177], v[166:169]
	ds_read_b128 v[2:5], v145 offset:8192
	ds_read_b128 v[22:25], v149 offset:8192
	ds_read_b128 v[30:33], v151 offset:8192
	ds_read_b128 v[174:177], v153 offset:8192
	v_mfma_f32_16x16x32_bf16 v[36:39], v[162:165], v[170:173], v[36:39]
	s_waitcnt lgkmcnt(0)
	v_mfma_f32_16x16x32_bf16 v[2:5], v[2:5], v[10:13], 0
	v_cmp_ge_i32_e32 vcc, s13, v121
	v_lshlrev_b32_e32 v40, 9, v34
	v_and_b32_e32 v42, 0x1fffe00, v40
	v_mfma_f32_16x16x32_bf16 v[2:5], v[22:25], v[6:9], v[2:5]
	v_lshl_add_u64 v[40:41], s[18:19], 0, v[42:43]
	s_mov_b32 m0, s44
	v_lshl_add_u64 v[40:41], v[40:41], 0, v[44:45]
	v_mfma_f32_16x16x32_bf16 v[22:25], v[30:33], v[10:13], 0
	v_mfma_f32_16x16x32_bf16 v[22:25], v[174:177], v[6:9], v[22:25]
	s_nop 2
	v_mul_f32_e32 v2, 0x3fb8aa3b, v2
	v_exp_f32_e32 v2, v2
	s_nop 0
	v_cndmask_b32_e32 v59, 0, v2, vcc
	v_mul_f32_e32 v2, 0x3fb8aa3b, v3
	v_mul_f32_e32 v22, 0x3fb8aa3b, v22
	v_exp_f32_e32 v22, v22
	v_exp_f32_e32 v2, v2
	v_mul_f32_e32 v3, 0x3fb8aa3b, v23
	v_exp_f32_e32 v3, v3
	v_cmp_ge_i32_e32 vcc, s13, v122
	s_nop 1
	v_cndmask_b32_e32 v155, 0, v22, vcc
	v_cmp_ge_i32_e32 vcc, s13, v123
	s_nop 1
	v_cndmask_b32_e32 v156, 0, v2, vcc
	v_cmp_ge_i32_e32 vcc, s13, v124
	v_mul_f32_e32 v2, 0x3fb8aa3b, v4
	v_exp_f32_e32 v2, v2
	v_cndmask_b32_e32 v157, 0, v3, vcc
	v_mul_f32_e32 v3, 0x3fb8aa3b, v24
	v_exp_f32_e32 v3, v3
	v_cmp_ge_i32_e32 vcc, s13, v125
	v_cvt_pk_bf16_f32 v162, v59, v156
	s_nop 1
	v_cndmask_b32_e32 v158, 0, v2, vcc
	v_cmp_ge_i32_e32 vcc, s13, v126
	v_mul_f32_e32 v2, 0x3fb8aa3b, v5
	v_exp_f32_e32 v2, v2
	v_cndmask_b32_e32 v160, 0, v3, vcc
	v_mul_f32_e32 v3, 0x3fb8aa3b, v25
	v_exp_f32_e32 v3, v3
	v_cmp_ge_i32_e32 vcc, s13, v127
	s_nop 1
	v_cndmask_b32_e32 v198, 0, v2, vcc
	v_cmp_ge_i32_e32 vcc, s13, v128
	v_cvt_pk_bf16_f32 v163, v158, v198
	v_cvt_pk_bf16_f32 v164, v155, v157
	s_nop 1
	v_cndmask_b32_e32 v199, 0, v3, vcc
	v_cvt_pk_bf16_f32 v165, v160, v199
	ds_read_b64_tr_b16 v[190:191], v89
	ds_read_b64_tr_b16 v[192:193], v90
	ds_read_b64_tr_b16 v[186:187], v91
	ds_read_b64_tr_b16 v[188:189], v92
	ds_read_b64_tr_b16 v[174:175], v93
	ds_read_b64_tr_b16 v[176:177], v94
	ds_read_b64_tr_b16 v[170:171], v95
	ds_read_b64_tr_b16 v[172:173], v96
	s_waitcnt lgkmcnt(0)
	s_waitcnt lgkmcnt(0)
	ds_read_b128 v[30:33], v28
	ds_read_b128 v[22:25], v28 offset:16
	ds_read_b128 v[2:5], v28 offset:32
	ds_read_b128 v[26:29], v28 offset:48
	global_load_lds_dwordx4 v[40:41], off
	v_lshl_add_u64 v[40:41], s[22:23], 0, v[42:43]
	v_lshl_add_u64 v[40:41], v[40:41], 0, v[52:53]
	s_mov_b32 m0, s58
	v_lshlrev_b32_sdwa v42, v64, v34 dst_sel:DWORD dst_unused:UNUSED_PAD src0_sel:DWORD src1_sel:WORD_1
	global_load_lds_dwordx4 v[40:41], off
	v_lshl_add_u64 v[40:41], s[18:19], 0, v[42:43]
	v_lshl_add_u64 v[40:41], v[40:41], 0, v[50:51]
	s_mov_b32 m0, s59
	v_lshlrev_b32_e32 v34, 9, v35
	global_load_lds_dwordx4 v[40:41], off
	v_lshl_add_u64 v[40:41], s[22:23], 0, v[42:43]
	v_lshl_add_u64 v[40:41], v[40:41], 0, v[52:53]
	s_mov_b32 m0, s60
	v_and_b32_e32 v42, 0x1fffe00, v34
	global_load_lds_dwordx4 v[40:41], off
	v_lshl_add_u64 v[40:41], s[18:19], 0, v[42:43]
	v_lshl_add_u64 v[40:41], v[40:41], 0, v[48:49]
	s_mov_b32 m0, s61
	v_mfma_f32_16x16x32_bf16 v[182:185], v[162:165], v[190:193], v[182:185]
	global_load_lds_dwordx4 v[40:41], off
	v_lshl_add_u64 v[40:41], s[22:23], 0, v[42:43]
	v_lshlrev_b32_sdwa v42, v64, v35 dst_sel:DWORD dst_unused:UNUSED_PAD src0_sel:DWORD src1_sel:WORD_1
	v_lshl_add_u64 v[40:41], v[40:41], 0, v[52:53]
	s_mov_b32 m0, s64
	v_lshl_add_u64 v[34:35], s[18:19], 0, v[42:43]
	global_load_lds_dwordx4 v[40:41], off
	v_lshl_add_u64 v[34:35], v[34:35], 0, v[46:47]
	s_mov_b32 m0, s65
	v_mfma_f32_16x16x32_bf16 v[178:181], v[162:165], v[186:189], v[178:181]
	global_load_lds_dwordx4 v[34:35], off
	v_lshl_add_u64 v[34:35], s[22:23], 0, v[42:43]
	v_lshl_add_u64 v[34:35], v[34:35], 0, v[52:53]
	s_mov_b32 m0, s66
	v_mfma_f32_16x16x32_bf16 v[166:169], v[162:165], v[174:177], v[166:169]
	global_load_lds_dwordx4 v[34:35], off
	s_waitcnt vmcnt(8)
	v_add_f32_e32 v34, v59, v155
	ds_read_b128 v[174:177], v145
	ds_read_b128 v[186:189], v149
	ds_read_b128 v[190:193], v151
	ds_read_b128 v[194:197], v153
	v_add_f32_e32 v34, v57, v34
	v_add_f32_e32 v35, v156, v157
	v_add_f32_e32 v34, v35, v34
	v_add_f32_e32 v35, v158, v160
	v_add_f32_e32 v40, v35, v34
	v_mfma_f32_16x16x32_bf16 v[34:37], v[162:165], v[170:173], v[36:39]
	s_nop 2
	v_add_f32_e32 v38, v198, v199
	v_add_f32_e32 v57, v38, v40
	s_waitcnt lgkmcnt(0)
	v_mfma_f32_16x16x32_bf16 v[38:41], v[174:177], v[10:13], 0
	v_cmp_ge_i32_e32 vcc, s13, v129
	s_mov_b32 m0, s46
	v_mfma_f32_16x16x32_bf16 v[38:41], v[186:189], v[6:9], v[38:41]
	v_mfma_f32_16x16x32_bf16 v[162:165], v[190:193], v[10:13], 0
	v_mfma_f32_16x16x32_bf16 v[162:165], v[194:197], v[6:9], v[162:165]
	s_nop 5
	v_mul_f32_e32 v38, 0x3fb8aa3b, v38
	v_exp_f32_e32 v38, v38
	s_nop 0
	v_cndmask_b32_e32 v59, 0, v38, vcc
	v_mul_f32_e32 v38, 0x3fb8aa3b, v39
	v_mul_f32_e32 v42, 0x3fb8aa3b, v162
	v_exp_f32_e32 v42, v42
	v_exp_f32_e32 v38, v38
	v_mul_f32_e32 v39, 0x3fb8aa3b, v163
	v_exp_f32_e32 v39, v39
	v_cmp_ge_i32_e32 vcc, s13, v130
	s_nop 1
	v_cndmask_b32_e32 v155, 0, v42, vcc
	v_cmp_ge_i32_e32 vcc, s13, v131
	v_lshlrev_b32_e32 v42, 9, v30
	v_and_b32_e32 v42, 0x1fffe00, v42
	v_cndmask_b32_e32 v158, 0, v38, vcc
	v_cmp_ge_i32_e32 vcc, s13, v132
	v_mul_f32_e32 v38, 0x3fb8aa3b, v40
	v_exp_f32_e32 v38, v38
	v_cndmask_b32_e32 v160, 0, v39, vcc
	v_mul_f32_e32 v39, 0x3fb8aa3b, v164
	v_exp_f32_e32 v39, v39
	v_cmp_ge_i32_e32 vcc, s13, v133
	v_lshl_add_u64 v[156:157], s[14:15], 0, v[42:43]
	v_lshl_add_u64 v[156:157], v[156:157], 0, v[44:45]
	v_cndmask_b32_e32 v190, 0, v38, vcc
	v_cmp_ge_i32_e32 vcc, s13, v134
	v_mul_f32_e32 v38, 0x3fb8aa3b, v41
	v_exp_f32_e32 v38, v38
	v_cndmask_b32_e32 v191, 0, v39, vcc
	v_mul_f32_e32 v39, 0x3fb8aa3b, v165
	v_exp_f32_e32 v39, v39
	v_cmp_ge_i32_e32 vcc, s13, v135
	s_nop 1
	v_cndmask_b32_e32 v194, 0, v38, vcc
	v_cmp_ge_i32_e32 vcc, s13, v136
	v_cvt_pk_bf16_f32 v38, v59, v158
	s_nop 1
	v_cndmask_b32_e32 v195, 0, v39, vcc
	v_cvt_pk_bf16_f32 v39, v190, v194
	v_cvt_pk_bf16_f32 v40, v155, v160
	v_cvt_pk_bf16_f32 v41, v191, v195
	ds_read_b64_tr_b16 v[186:187], v73
	ds_read_b64_tr_b16 v[188:189], v74
	ds_read_b64_tr_b16 v[174:175], v75
	ds_read_b64_tr_b16 v[176:177], v76
	ds_read_b64_tr_b16 v[170:171], v77
	ds_read_b64_tr_b16 v[172:173], v78
	ds_read_b64_tr_b16 v[162:163], v79
	ds_read_b64_tr_b16 v[164:165], v80
	s_waitcnt lgkmcnt(0)
	global_load_lds_dwordx4 v[156:157], off
	v_lshl_add_u64 v[156:157], s[16:17], 0, v[42:43]
	v_lshl_add_u64 v[156:157], v[156:157], 0, v[52:53]
	s_mov_b32 m0, s48
	v_lshlrev_b32_sdwa v42, v64, v30 dst_sel:DWORD dst_unused:UNUSED_PAD src0_sel:DWORD src1_sel:WORD_1
	global_load_lds_dwordx4 v[156:157], off
	v_lshl_add_u64 v[156:157], s[14:15], 0, v[42:43]
	v_lshl_add_u64 v[156:157], v[156:157], 0, v[50:51]
	s_mov_b32 m0, s49
	v_lshlrev_b32_e32 v30, 9, v31
	global_load_lds_dwordx4 v[156:157], off
	v_lshl_add_u64 v[156:157], s[16:17], 0, v[42:43]
	v_lshl_add_u64 v[156:157], v[156:157], 0, v[52:53]
	s_mov_b32 m0, s50
	v_and_b32_e32 v42, 0x1fffe00, v30
	global_load_lds_dwordx4 v[156:157], off
	v_lshl_add_u64 v[156:157], s[14:15], 0, v[42:43]
	v_lshl_add_u64 v[156:157], v[156:157], 0, v[48:49]
	s_mov_b32 m0, s51
	v_mfma_f32_16x16x32_bf16 v[182:185], v[38:41], v[186:189], v[182:185]
	global_load_lds_dwordx4 v[156:157], off
	v_lshl_add_u64 v[156:157], s[16:17], 0, v[42:43]
	v_lshlrev_b32_sdwa v42, v64, v31 dst_sel:DWORD dst_unused:UNUSED_PAD src0_sel:DWORD src1_sel:WORD_1
	v_lshl_add_u64 v[156:157], v[156:157], 0, v[52:53]
	s_mov_b32 m0, s52
	v_lshl_add_u64 v[30:31], s[14:15], 0, v[42:43]
	global_load_lds_dwordx4 v[156:157], off
	v_lshl_add_u64 v[30:31], v[30:31], 0, v[46:47]
	s_mov_b32 m0, s53
	v_mfma_f32_16x16x32_bf16 v[174:177], v[38:41], v[174:177], v[178:181]
	global_load_lds_dwordx4 v[30:31], off
	v_lshl_add_u64 v[30:31], s[16:17], 0, v[42:43]
	v_lshl_add_u64 v[30:31], v[30:31], 0, v[52:53]
	s_mov_b32 m0, s54
	v_mfma_f32_16x16x32_bf16 v[166:169], v[38:41], v[170:173], v[166:169]
	global_load_lds_dwordx4 v[30:31], off
	v_add_f32_e32 v30, v59, v155
	v_add_f32_e32 v30, v57, v30
	v_add_f32_e32 v31, v158, v160
	s_waitcnt vmcnt(8)
	v_add_f32_e32 v30, v31, v30
	v_add_f32_e32 v31, v190, v191
	ds_read_b128 v[170:173], v145 offset:8192
	ds_read_b128 v[178:181], v149 offset:8192
	ds_read_b128 v[186:189], v151 offset:8192
	ds_read_b128 v[190:193], v153 offset:8192
	v_add_f32_e32 v30, v31, v30
	v_add_f32_e32 v31, v194, v195
	v_add_f32_e32 v30, v31, v30
	v_mfma_f32_16x16x32_bf16 v[162:165], v[38:41], v[162:165], v[34:37]
	s_waitcnt lgkmcnt(0)
	v_mfma_f32_16x16x32_bf16 v[34:37], v[170:173], v[10:13], 0
	v_cmp_ge_i32_e32 vcc, s13, v137
	v_mfma_f32_16x16x32_bf16 v[10:13], v[186:189], v[10:13], 0
	v_mfma_f32_16x16x32_bf16 v[34:37], v[178:181], v[6:9], v[34:37]
	v_mfma_f32_16x16x32_bf16 v[6:9], v[190:193], v[6:9], v[10:13]
	s_nop 6
	v_mul_f32_e32 v31, 0x3fb8aa3b, v34
	v_exp_f32_e32 v31, v31
	v_mul_f32_e32 v6, 0x3fb8aa3b, v6
	v_exp_f32_e32 v6, v6
	v_mul_f32_e32 v12, 0x3fb8aa3b, v35
	v_exp_f32_e32 v12, v12
	v_mul_f32_e32 v7, 0x3fb8aa3b, v7
	v_exp_f32_e32 v7, v7
	v_cndmask_b32_e32 v10, 0, v31, vcc
	v_cmp_ge_i32_e32 vcc, s13, v138
	v_mul_f32_e32 v8, 0x3fb8aa3b, v8
	v_exp_f32_e32 v8, v8
	v_cndmask_b32_e32 v11, 0, v6, vcc
	v_cmp_ge_i32_e32 vcc, s13, v139
	v_add_f32_e32 v6, v10, v11
	v_add_f32_e32 v6, v30, v6
	v_cndmask_b32_e32 v12, 0, v12, vcc
	v_cmp_ge_i32_e32 vcc, s13, v140
	s_nop 1
	v_cndmask_b32_e32 v13, 0, v7, vcc
	v_add_f32_e32 v7, v12, v13
	v_add_f32_e32 v6, v7, v6
	v_mul_f32_e32 v7, 0x3fb8aa3b, v36
	v_exp_f32_e32 v7, v7
	v_cmp_ge_i32_e32 vcc, s13, v141
	s_nop 1
	v_cndmask_b32_e32 v7, 0, v7, vcc
	v_cmp_ge_i32_e32 vcc, s13, v142
	s_nop 1
	v_cndmask_b32_e32 v30, 0, v8, vcc
	v_add_f32_e32 v8, v7, v30
	v_add_f32_e32 v31, v8, v6
	v_mul_f32_e32 v6, 0x3fb8aa3b, v37
	v_exp_f32_e32 v6, v6
	v_mul_f32_e32 v8, 0x3fb8aa3b, v9
	v_exp_f32_e32 v8, v8
	v_cmp_ge_i32_e32 vcc, s13, v143
	s_nop 1
	v_cndmask_b32_e32 v42, 0, v6, vcc
	v_cmp_ge_i32_e32 vcc, s13, v144
	v_cvt_pk_bf16_f32 v6, v10, v12
	v_cvt_pk_bf16_f32 v7, v7, v42
	s_nop 1
	v_cndmask_b32_e32 v57, 0, v8, vcc
.Lg_join:
	v_cvt_pk_bf16_f32 v8, v11, v13
	v_cvt_pk_bf16_f32 v9, v30, v57
	v_add_f32_e32 v30, v42, v57
	v_and_b32_e32 v42, 64, v147
	v_add_f32_e32 v30, v30, v31
	v_xor_b32_e32 v31, 16, v147
	v_add_u32_e32 v42, 64, v42
	v_cmp_lt_i32_e32 vcc, v31, v42
	ds_read_b64_tr_b16 v[10:11], v89
	ds_read_b64_tr_b16 v[12:13], v90
	ds_read_b64_tr_b16 v[38:39], v91
	ds_read_b64_tr_b16 v[40:41], v92
	ds_read_b64_tr_b16 v[34:35], v93
	ds_read_b64_tr_b16 v[36:37], v94
	ds_read_b64_tr_b16 v[170:171], v95
	ds_read_b64_tr_b16 v[172:173], v96
	s_waitcnt lgkmcnt(0)
	s_nop 0
	v_mfma_f32_16x16x32_bf16 v[10:13], v[6:9], v[10:13], v[182:185]
	v_cndmask_b32_e32 v31, v147, v31, vcc
	v_lshlrev_b32_e32 v31, 2, v31
	ds_bpermute_b32 v31, v31, v30
	v_mfma_f32_16x16x32_bf16 v[38:41], v[6:9], v[38:41], v[174:177]
	s_waitcnt lgkmcnt(0)
	v_add_f32_e32 v30, v30, v31
	v_xor_b32_e32 v31, 32, v147
	v_cmp_lt_i32_e32 vcc, v31, v42
	v_mfma_f32_16x16x32_bf16 v[34:37], v[6:9], v[34:37], v[166:169]
	s_nop 0
	v_cndmask_b32_e32 v31, v147, v31, vcc
	v_lshlrev_b32_e32 v31, 2, v31
	ds_bpermute_b32 v31, v31, v30
	v_mfma_f32_16x16x32_bf16 v[6:9], v[6:9], v[170:173], v[162:165]
	s_waitcnt lgkmcnt(0)
	v_add_f32_e32 v57, v30, v31
	v_lshlrev_b32_e32 v30, 2, v147
	v_and_b32_e32 v59, 0x100, v30
	ds_bpermute_b32 v30, v59, v57
	ds_bpermute_b32 v31, v59, v57 offset:4
	ds_bpermute_b32 v42, v59, v57 offset:8
	ds_bpermute_b32 v57, v59, v57 offset:12
	s_and_saveexec_b64 s[14:15], s[6:7]
	s_cbranch_execz .LBB0_977
	s_waitcnt lgkmcnt(0)
	v_div_scale_f32 v59, s[16:17], v57, v57, 1.0
	v_rcp_f32_e32 v155, v59
	s_ashr_i32 s13, s12, 31
	s_lshl_b64 s[10:11], s[10:11], 24
	v_fma_f32 v156, -v59, v155, 1.0
	v_fmac_f32_e32 v155, v156, v155
	v_div_scale_f32 v156, vcc, 1.0, v57, 1.0
	v_mul_f32_e32 v157, v156, v155
	v_fma_f32 v158, -v59, v157, v156
	v_fmac_f32_e32 v157, v158, v155
	v_fma_f32 v59, -v59, v157, v156
	v_div_scale_f32 v156, s[16:17], v42, v42, 1.0
	v_rcp_f32_e32 v158, v156
	v_div_fmas_f32 v59, v59, v155, v157
	v_div_fixup_f32 v57, v59, v57, 1.0
	v_fma_f32 v59, -v156, v158, 1.0
	v_fmac_f32_e32 v158, v59, v158
	v_div_scale_f32 v59, vcc, 1.0, v42, 1.0
	v_mul_f32_e32 v155, v59, v158
	v_fma_f32 v157, -v156, v155, v59
	v_fmac_f32_e32 v155, v157, v158
	v_fma_f32 v59, -v156, v155, v59
	v_div_scale_f32 v156, s[16:17], v31, v31, 1.0
	v_rcp_f32_e32 v157, v156
	v_div_fmas_f32 v59, v59, v158, v155
	v_div_fixup_f32 v42, v59, v42, 1.0
	v_fma_f32 v59, -v156, v157, 1.0
	v_fmac_f32_e32 v157, v59, v157
	v_div_scale_f32 v59, vcc, 1.0, v31, 1.0
	v_mul_f32_e32 v155, v59, v157
	v_fma_f32 v158, -v156, v155, v59
	v_fmac_f32_e32 v155, v158, v157
	v_fma_f32 v59, -v156, v155, v59
	v_div_scale_f32 v156, s[16:17], v30, v30, 1.0
	v_rcp_f32_e32 v158, v156
	v_div_fmas_f32 v59, v59, v157, v155
	v_div_fixup_f32 v155, v59, v31, 1.0
	s_add_u32 s16, s62, s10
	v_fma_f32 v31, -v156, v158, 1.0
	v_fmac_f32_e32 v158, v31, v158
	v_div_scale_f32 v31, vcc, 1.0, v30, 1.0
	v_mul_f32_e32 v59, v31, v158
	v_fma_f32 v157, -v156, v59, v31
	v_fmac_f32_e32 v59, v157, v158
	v_fma_f32 v31, -v156, v59, v31
	v_div_fmas_f32 v31, v31, v158, v59
	s_addc_u32 s17, s63, s11
	s_lshl_b64 s[10:11], s[12:13], 11
	v_div_fixup_f32 v156, v31, v30, 1.0
	s_add_u32 s10, s16, s10
	s_addc_u32 s11, s17, s11
	v_mov_b32_e32 v59, v43
	v_mul_f32_e32 v10, v10, v156
	v_lshl_add_u64 v[30:31], s[10:11], 0, v[58:59]
	v_bfe_u32 v59, v10, 16, 1
	s_lshl_b32 s8, s8, 9
	v_add3_u32 v10, v10, v59, s67
	v_lshl_add_u64 v[30:31], v[30:31], 0, s[8:9]
	global_store_short_d16_hi v[30:31], v10, off
	v_mul_f32_e32 v10, v11, v155
	v_bfe_u32 v11, v10, 16, 1
	v_add3_u32 v10, v10, v11, s67
	global_store_short_d16_hi v[30:31], v10, off offset:128
	v_mul_f32_e32 v10, v12, v42
	v_bfe_u32 v11, v10, 16, 1
	v_add3_u32 v10, v10, v11, s67
	global_store_short_d16_hi v[30:31], v10, off offset:256
	v_mul_f32_e32 v10, v13, v57
	v_bfe_u32 v11, v10, 16, 1
	v_add3_u32 v10, v10, v11, s67
	global_store_short_d16_hi v[30:31], v10, off offset:384
	v_mul_f32_e32 v10, v38, v156
	v_bfe_u32 v11, v10, 16, 1
	v_add3_u32 v10, v10, v11, s67
	global_store_short_d16_hi v[30:31], v10, off offset:32
	v_mul_f32_e32 v10, v39, v155
	v_bfe_u32 v11, v10, 16, 1
	v_add3_u32 v10, v10, v11, s67
	global_store_short_d16_hi v[30:31], v10, off offset:160
	v_mul_f32_e32 v10, v40, v42
	v_bfe_u32 v11, v10, 16, 1
	v_add3_u32 v10, v10, v11, s67
	global_store_short_d16_hi v[30:31], v10, off offset:288
	v_mul_f32_e32 v10, v41, v57
	v_bfe_u32 v11, v10, 16, 1
	v_add3_u32 v10, v10, v11, s67
	global_store_short_d16_hi v[30:31], v10, off offset:416
	v_mul_f32_e32 v10, v34, v156
	v_bfe_u32 v11, v10, 16, 1
	v_add3_u32 v10, v10, v11, s67
	global_store_short_d16_hi v[30:31], v10, off offset:64
	v_mul_f32_e32 v10, v35, v155
	v_bfe_u32 v11, v10, 16, 1
	v_add3_u32 v10, v10, v11, s67
	global_store_short_d16_hi v[30:31], v10, off offset:192
	v_mul_f32_e32 v10, v36, v42
	v_bfe_u32 v11, v10, 16, 1
	v_add3_u32 v10, v10, v11, s67
	global_store_short_d16_hi v[30:31], v10, off offset:320
	v_mul_f32_e32 v10, v37, v57
	v_bfe_u32 v11, v10, 16, 1
	v_add3_u32 v10, v10, v11, s67
	v_mul_f32_e32 v6, v6, v156
	global_store_short_d16_hi v[30:31], v10, off offset:448
	v_bfe_u32 v10, v6, 16, 1
	v_add3_u32 v6, v6, v10, s67
	global_store_short_d16_hi v[30:31], v6, off offset:96
	v_mul_f32_e32 v6, v7, v155
	v_bfe_u32 v7, v6, 16, 1
	v_add3_u32 v6, v6, v7, s67
	global_store_short_d16_hi v[30:31], v6, off offset:224
	v_mul_f32_e32 v6, v8, v42
	v_bfe_u32 v7, v6, 16, 1
	v_add3_u32 v6, v6, v7, s67
	global_store_short_d16_hi v[30:31], v6, off offset:352
	v_mul_f32_e32 v6, v9, v57
	v_bfe_u32 v7, v6, 16, 1
	v_add3_u32 v6, v6, v7, s67
	global_store_short_d16_hi v[30:31], v6, off offset:480
	s_branch .LBB0_977

.LBB0_1032:
	s_or_b64 exec, exec, s[4:5]
	s_add_u32 s12, s28, 0x1c000000
	s_addc_u32 s13, s29, 0
	s_waitcnt lgkmcnt(0)
	v_lshlrev_b32_e32 v1, 1, v212
	s_cmpk_lt_i32 s2, 0x200
	v_readfirstlane_b32 s16, v202
	s_cselect_b64 s[6:7], -1, 0
	s_cmpk_gt_i32 s2, 0x1ff
	v_bitop3_b32 v178, v1, v161, v159 bitop3:0x36
	s_barrier
	s_nop 0
	s_nop 0
	s_nop 0
	s_nop 0
	s_nop 0
	s_nop 0
	s_nop 0
	s_nop 0
	s_nop 0
	s_nop 0
	s_nop 0
	s_cbranch_scc1 .LBB0_1056
	s_ashr_i32 s37, s2, 31
	s_lshr_b32 s4, s37, 29
	s_add_i32 s8, s2, s4
	s_and_b32 s4, s8, -8
	s_sub_i32 s10, s2, s4
	s_cmp_gt_i32 s10, -1
	s_cbranch_scc0 .LBB0_1035
	s_lshl_b32 s9, s10, 6
	s_cbranch_execz .LBB0_1036
	s_branch .LBB0_1037
